# k16 plus loop-edge rotation variant: counter/address scalar block placed at the end of the last load segment (before its barrier) instead of inside the MFMA block, 3 StaticOrder GEMM loops
# baseline (speedup 1.0000x reference)
;     __device__ bool next(int i, Unit& u) const { if (i >= 2) return false; const int x = c & 7, j = c >> 3; u.pm = 32 * i + 4 * x + (j & 3); u.pn = j >> 2; return true; }
; #define PG8_STAGE(bufoff, gbase, voff) do { _Pragma("unroll") for (int _i = 0; _i < 2; ++_i) \
;         __builtin_amdgcn_global_load_lds((const unsigned*)((const char*)(gbase) + (voff)[_i]), (LAS unsigned*)(lds + (bufoff) + ldsw + _i * 8192), 16, 0, 0); } while (0)
; #define PG8_LDA(dst, b, h) do { _Pragma("unroll") for (int m = 0; m < 4; ++m) _Pragma("unroll") for (int k = 0; k < 2; ++k) dst[m][k] = *(const LAS bf16x8*)(lds + PG8_SA(b, h) + aoff + m * 2048 + k * 1024); } while (0)
; #define PG8_LDB(dst, b, h) do { _Pragma("unroll") for (int n = 0; n < 2; ++n) _Pragma("unroll") for (int k = 0; k < 2; ++k) dst[n][k] = *(const LAS bf16x8*)(lds + PG8_SB(b, h) + boff + n * 2048 + k * 1024); } while (0)
; #define PG8_WAIT_V(n) asm volatile("s_waitcnt vmcnt(" #n ")" ::: "memory")
; #define PG8_WAIT_L(n) asm volatile("s_waitcnt lgkmcnt(" #n ")" ::: "memory")
; #define PG8_BAR __builtin_amdgcn_s_barrier()
; template <class Epi, class Sched, bool ALIGN_EPI = true>
; __device__ __forceinline__ void gemm_phase(LAS unsigned char* lds, const Gemm g, const Sched& S, const Epi& E) {
;     ...
;         const bool has_next = S.next(ui + 1, nxt);
;         const char* nA = has_next ? (const char*)g.A + ((size_t)nxt.pm * BM * g.lda + (size_t)nxt.pn * g.a_pn_off) * 2 : cA; const char* nB = has_next ? (const char*)g.Bt + (size_t)nxt.pn * BM * g.ldb * 2 : cB;
;         for (int t = 0; t < nt; t += 2) {
;             const bool last = (t == nt - 2);
;             const char* a1 = cA + (size_t)(t + 1) * kstep;
;             const char* a2 = last ? nA : cA + (size_t)(t + 2) * kstep; const char* b2 = last ? nB : cB + (size_t)(t + 2) * kstep;
;             const char* a3 = a2 + kstep; const char* b3 = b2 + kstep;
;             PG8_LDB(B0, 0, 0); PG8_LDB(B1, 0, 1); PG8_SCHED; PG8_LDA(At, 0, 0); PG8_STAGE(PG8_SA(1, 1), a1 + hA, voffA);
;             PG8_WAIT_V(8); PG8_WAIT_L(0); PG8_BAR; PG8_MMA(0, 0, At, B0); PG8_MMA(0, 1, At, B1); PG8_BAR; PG8_SCHED;
;             PG8_LDA(At, 0, 1); PG8_STAGE(PG8_SB(0, 0), b2, voffB); PG8_STAGE(PG8_SB(0, 1), b2 + hB, voffB); PG8_STAGE(PG8_SA(0, 0), a2, voffA);
;             PG8_WAIT_V(8); PG8_WAIT_L(0); PG8_BAR; PG8_MMA(1, 0, At, B0); PG8_MMA(1, 1, At, B1); PG8_BAR; PG8_SCHED;
.LBB0_76:
	s_ashr_i32 s15, s14, 31
	s_lshl_b64 s[18:19], s[14:15], 20
	s_add_u32 s38, s46, s18
	s_addc_u32 s39, s47, s19
	s_and_b64 s[18:19], s[4:5], exec
	s_cselect_b32 s15, s39, s7
	s_cselect_b32 s17, s38, s6
	s_ashr_i32 s13, s12, 31
	s_lshl_b64 s[18:19], s[12:13], 20
	s_add_u32 s40, s53, s18
	s_addc_u32 s41, s58, s19
	s_and_b64 s[18:19], s[4:5], exec
	s_cselect_b32 s13, s41, s43
	s_cselect_b32 s18, s40, s42
	s_add_u32 s6, s6, 0x80080
	s_addc_u32 s7, s7, 0
	s_add_u32 s19, s42, 0x100
	s_addc_u32 s24, s43, 0
	s_mov_b32 s25, -2
	s_add_u32 s26, s6, 0xfff80080
	s_addc_u32 s27, s7, -1
	s_add_i32 s30, 0, 0x10000
	s_cmp_eq_u32 s25, 28
	s_cselect_b32 s45, s15, s27
	s_cselect_b32 s44, s17, s26
	s_cselect_b32 s43, s13, s24
	s_cselect_b32 s42, s18, s19
	s_add_i32 s31, 0, 0x14000
	v_add_u32_e32 v144, s30, v166
	v_add_u32_e32 v156, s31, v166
	ds_read_b128 v[132:135], v144
	ds_read_b128 v[136:139], v144 offset:1024
	ds_read_b128 v[140:143], v144 offset:2048
	ds_read_b128 v[144:147], v144 offset:3072
	ds_read_b128 v[170:173], v156
	ds_read_b128 v[174:177], v156 offset:1024
	ds_read_b128 v[178:181], v156 offset:2048
	ds_read_b128 v[182:185], v156 offset:3072
	v_lshl_add_u64 v[156:157], s[6:7], 0, v[152:153]
	s_add_i32 m0, s60, 0xc000
	ds_read_b128 v[186:189], v168
	ds_read_b128 v[190:193], v168 offset:1024
	ds_read_b128 v[194:197], v168 offset:2048
	ds_read_b128 v[204:207], v168 offset:3072
	ds_read_b128 v[208:211], v168 offset:4096
	ds_read_b128 v[212:215], v168 offset:5120
	ds_read_b128 v[216:219], v168 offset:6144
	ds_read_b128 v[220:223], v168 offset:7168
	global_load_lds_dwordx4 v[156:157], off
	v_lshl_add_u64 v[156:157], s[6:7], 0, v[154:155]
	s_add_i32 m0, s60, 0xe000
	s_nop 0
	global_load_lds_dwordx4 v[156:157], off
	s_waitcnt vmcnt(8)
	s_waitcnt lgkmcnt(0)
	s_barrier
	s_setprio 1
	s_waitcnt lgkmcnt(0)
	v_mfma_f32_16x16x32_bf16 v[128:131], v[132:135], v[186:189], 0
	v_mfma_f32_16x16x32_bf16 v[128:131], v[136:139], v[190:193], v[128:131]
	v_mfma_f32_16x16x32_bf16 v[124:127], v[140:143], v[186:189], 0
	v_mfma_f32_16x16x32_bf16 v[124:127], v[144:147], v[190:193], v[124:127]
	v_mfma_f32_16x16x32_bf16 v[116:119], v[132:135], v[194:197], 0
	v_mfma_f32_16x16x32_bf16 v[116:119], v[136:139], v[204:207], v[116:119]
	v_mfma_f32_16x16x32_bf16 v[112:115], v[140:143], v[194:197], 0
	v_mfma_f32_16x16x32_bf16 v[112:115], v[144:147], v[204:207], v[112:115]
	v_mfma_f32_16x16x32_bf16 v[104:107], v[132:135], v[208:211], 0
	v_mfma_f32_16x16x32_bf16 v[104:107], v[136:139], v[212:215], v[104:107]
	v_mfma_f32_16x16x32_bf16 v[96:99], v[140:143], v[208:211], 0
	v_mfma_f32_16x16x32_bf16 v[96:99], v[144:147], v[212:215], v[96:99]
	v_mfma_f32_16x16x32_bf16 v[88:91], v[132:135], v[216:219], 0
	v_mfma_f32_16x16x32_bf16 v[88:91], v[136:139], v[220:223], v[88:91]
	v_mfma_f32_16x16x32_bf16 v[80:83], v[140:143], v[216:219], 0
	v_mfma_f32_16x16x32_bf16 v[80:83], v[144:147], v[220:223], v[80:83]
	s_setprio 0
	s_setprio 1
	v_mfma_f32_16x16x32_bf16 v[120:123], v[170:173], v[186:189], 0
	v_mfma_f32_16x16x32_bf16 v[120:123], v[174:177], v[190:193], v[120:123]
	v_mfma_f32_16x16x32_bf16 v[108:111], v[178:181], v[186:189], 0
	v_mfma_f32_16x16x32_bf16 v[108:111], v[182:185], v[190:193], v[108:111]
	v_mfma_f32_16x16x32_bf16 v[100:103], v[170:173], v[194:197], 0
	v_mfma_f32_16x16x32_bf16 v[100:103], v[174:177], v[204:207], v[100:103]
	v_mfma_f32_16x16x32_bf16 v[92:95], v[178:181], v[194:197], 0
	v_mfma_f32_16x16x32_bf16 v[92:95], v[182:185], v[204:207], v[92:95]
	v_mfma_f32_16x16x32_bf16 v[84:87], v[170:173], v[208:211], 0
	v_mfma_f32_16x16x32_bf16 v[84:87], v[174:177], v[212:215], v[84:87]
	v_mfma_f32_16x16x32_bf16 v[76:79], v[178:181], v[208:211], 0
	v_mfma_f32_16x16x32_bf16 v[76:79], v[182:185], v[212:215], v[76:79]
	v_mfma_f32_16x16x32_bf16 v[72:75], v[170:173], v[216:219], 0
	v_mfma_f32_16x16x32_bf16 v[72:75], v[174:177], v[220:223], v[72:75]
	s_setprio 2
	s_barrier
	v_mfma_f32_16x16x32_bf16 v[68:71], v[178:181], v[216:219], 0
	v_mfma_f32_16x16x32_bf16 v[68:71], v[182:185], v[220:223], v[68:71]
	s_setprio 0
	s_add_i32 s26, s30, s59
	v_lshl_add_u64 v[156:157], s[42:43], 0, v[2:3]
	s_mov_b32 m0, s26
	ds_read_b128 v[186:189], v168 offset:16384
	ds_read_b128 v[190:193], v168 offset:17408
	ds_read_b128 v[194:197], v168 offset:18432
	ds_read_b128 v[204:207], v168 offset:19456
	ds_read_b128 v[208:211], v168 offset:20480
	ds_read_b128 v[212:215], v168 offset:21504
	ds_read_b128 v[216:219], v168 offset:22528
	ds_read_b128 v[220:223], v168 offset:23552
	global_load_lds_dwordx4 v[156:157], off
	s_add_i32 m0, s26, 0x2000
	s_add_u32 s26, s42, 0x80000
	v_lshl_add_u64 v[164:165], s[42:43], 0, v[0:1]
	s_addc_u32 s27, s43, 0
	s_add_i32 s30, s31, s59
	global_load_lds_dwordx4 v[164:165], off
	v_lshl_add_u64 v[224:225], s[26:27], 0, v[2:3]
	s_mov_b32 m0, s30
	v_lshl_add_u64 v[226:227], s[44:45], 0, v[148:149]
	global_load_lds_dwordx4 v[224:225], off
	v_lshl_add_u64 v[224:225], s[26:27], 0, v[0:1]
	s_add_i32 m0, s30, 0x2000
	s_nop 0
	global_load_lds_dwordx4 v[224:225], off
	v_lshl_add_u64 v[224:225], s[44:45], 0, v[150:151]
	s_mov_b32 m0, s60
	s_nop 0
	global_load_lds_dwordx4 v[224:225], off
	s_mov_b32 m0, s61
	s_nop 0
	global_load_lds_dwordx4 v[226:227], off
	s_waitcnt vmcnt(8)
	s_waitcnt lgkmcnt(0)
	s_barrier
; #define PG8_STAGE(bufoff, gbase, voff) do { _Pragma("unroll") for (int _i = 0; _i < 2; ++_i) \
;         __builtin_amdgcn_global_load_lds((const unsigned*)((const char*)(gbase) + (voff)[_i]), (LAS unsigned*)(lds + (bufoff) + ldsw + _i * 8192), 16, 0, 0); } while (0)
; #define PG8_LDA(dst, b, h) do { _Pragma("unroll") for (int m = 0; m < 4; ++m) _Pragma("unroll") for (int k = 0; k < 2; ++k) dst[m][k] = *(const LAS bf16x8*)(lds + PG8_SA(b, h) + aoff + m * 2048 + k * 1024); } while (0)
; #define PG8_LDB(dst, b, h) do { _Pragma("unroll") for (int n = 0; n < 2; ++n) _Pragma("unroll") for (int k = 0; k < 2; ++k) dst[n][k] = *(const LAS bf16x8*)(lds + PG8_SB(b, h) + boff + n * 2048 + k * 1024); } while (0)
; #define PG8_MMA(ai, bj, At, Bt) do { __builtin_amdgcn_s_setprio(1); _Pragma("unroll") for (int m = 0; m < 4; ++m) _Pragma("unroll") for (int n = 0; n < 2; ++n) _Pragma("unroll") for (int k = 0; k < 2; ++k) \
;         acc[ai][bj][m][n] = __builtin_amdgcn_mfma_f32_16x16x32_bf16(Bt[n][k], At[m][k], acc[ai][bj][m][n], 0, 0, 0); __builtin_amdgcn_s_setprio(0); } while (0)
; #define PG8_WAIT_V(n) asm volatile("s_waitcnt vmcnt(" #n ")" ::: "memory")
; #define PG8_WAIT_L(n) asm volatile("s_waitcnt lgkmcnt(" #n ")" ::: "memory")
; #define PG8_BAR __builtin_amdgcn_s_barrier()
; #define PG8_SCHED __builtin_amdgcn_sched_barrier(0)
; template <class Epi, class Sched, bool ALIGN_EPI = true>
; __device__ __forceinline__ void gemm_phase(LAS unsigned char* lds, const Gemm g, const Sched& S, const Epi& E) {
;     ...
;             PG8_WAIT_V(8); PG8_WAIT_L(0); PG8_BAR; PG8_MMA(1, 0, At, B0); PG8_MMA(1, 1, At, B1); PG8_BAR; PG8_SCHED;
;             PG8_LDB(B0, 1, 0); PG8_LDB(B1, 1, 1); PG8_SCHED; PG8_LDA(At, 1, 0); PG8_STAGE(PG8_SA(0, 1), a2 + hA, voffA);
;             PG8_WAIT_V(8); PG8_WAIT_L(0); PG8_BAR; PG8_MMA(0, 0, At, B0); PG8_MMA(0, 1, At, B1); PG8_BAR; PG8_SCHED;
;             PG8_LDA(At, 1, 1); PG8_STAGE(PG8_SB(1, 0), b3, voffB); PG8_STAGE(PG8_SB(1, 1), b3 + hB, voffB); PG8_STAGE(PG8_SA(1, 0), a3, voffA);
;             PG8_WAIT_V(8); PG8_WAIT_L(0); PG8_BAR; PG8_MMA(1, 0, At, B0); PG8_MMA(1, 1, At, B1); PG8_BAR; PG8_SCHED;
	s_setprio 1
	s_waitcnt lgkmcnt(0)
	v_mfma_f32_16x16x32_bf16 v[64:67], v[132:135], v[186:189], 0
	v_mfma_f32_16x16x32_bf16 v[64:67], v[136:139], v[190:193], v[64:67]
	v_mfma_f32_16x16x32_bf16 v[60:63], v[140:143], v[186:189], 0
	v_mfma_f32_16x16x32_bf16 v[60:63], v[144:147], v[190:193], v[60:63]
	v_mfma_f32_16x16x32_bf16 v[56:59], v[132:135], v[194:197], 0
	v_mfma_f32_16x16x32_bf16 v[56:59], v[136:139], v[204:207], v[56:59]
	v_mfma_f32_16x16x32_bf16 v[48:51], v[140:143], v[194:197], 0
	v_mfma_f32_16x16x32_bf16 v[48:51], v[144:147], v[204:207], v[48:51]
	v_mfma_f32_16x16x32_bf16 v[40:43], v[132:135], v[208:211], 0
	v_mfma_f32_16x16x32_bf16 v[40:43], v[136:139], v[212:215], v[40:43]
	v_mfma_f32_16x16x32_bf16 v[32:35], v[140:143], v[208:211], 0
	v_mfma_f32_16x16x32_bf16 v[32:35], v[144:147], v[212:215], v[32:35]
	v_mfma_f32_16x16x32_bf16 v[24:27], v[132:135], v[216:219], 0
	v_mfma_f32_16x16x32_bf16 v[24:27], v[136:139], v[220:223], v[24:27]
	v_mfma_f32_16x16x32_bf16 v[16:19], v[140:143], v[216:219], 0
	v_mfma_f32_16x16x32_bf16 v[16:19], v[144:147], v[220:223], v[16:19]
	s_setprio 0
	s_setprio 1
	v_mfma_f32_16x16x32_bf16 v[52:55], v[170:173], v[186:189], 0
	v_mfma_f32_16x16x32_bf16 v[52:55], v[174:177], v[190:193], v[52:55]
	v_mfma_f32_16x16x32_bf16 v[44:47], v[178:181], v[186:189], 0
	v_mfma_f32_16x16x32_bf16 v[44:47], v[182:185], v[190:193], v[44:47]
	v_mfma_f32_16x16x32_bf16 v[36:39], v[170:173], v[194:197], 0
	v_mfma_f32_16x16x32_bf16 v[36:39], v[174:177], v[204:207], v[36:39]
	v_mfma_f32_16x16x32_bf16 v[28:31], v[178:181], v[194:197], 0
	v_mfma_f32_16x16x32_bf16 v[28:31], v[182:185], v[204:207], v[28:31]
	v_mfma_f32_16x16x32_bf16 v[20:23], v[170:173], v[208:211], 0
	v_mfma_f32_16x16x32_bf16 v[20:23], v[174:177], v[212:215], v[20:23]
	v_mfma_f32_16x16x32_bf16 v[12:15], v[178:181], v[208:211], 0
	v_mfma_f32_16x16x32_bf16 v[12:15], v[182:185], v[212:215], v[12:15]
	v_mfma_f32_16x16x32_bf16 v[8:11], v[170:173], v[216:219], 0
	v_mfma_f32_16x16x32_bf16 v[8:11], v[174:177], v[220:223], v[8:11]
	s_setprio 2
	s_barrier
	v_mfma_f32_16x16x32_bf16 v[4:7], v[178:181], v[216:219], 0
	v_mfma_f32_16x16x32_bf16 v[4:7], v[182:185], v[220:223], v[4:7]
	s_setprio 0
	s_add_i32 s30, 0, 0x18000
	s_add_i32 s31, 0, 0x1c000
	v_add_u32_e32 v144, s30, v166
	v_add_u32_e32 v160, s31, v166
	ds_read_b128 v[132:135], v144
	ds_read_b128 v[136:139], v144 offset:1024
	ds_read_b128 v[140:143], v144 offset:2048
	ds_read_b128 v[144:147], v144 offset:3072
	ds_read_b128 v[170:173], v160
	ds_read_b128 v[174:177], v160 offset:1024
	ds_read_b128 v[178:181], v160 offset:2048
	ds_read_b128 v[182:185], v160 offset:3072
	s_add_u32 s26, s44, 0x80000
	s_addc_u32 s27, s45, 0
	s_mov_b32 m0, s62
	v_lshl_add_u64 v[228:229], s[26:27], 0, v[150:151]
	ds_read_b128 v[186:189], v168 offset:32768
	ds_read_b128 v[190:193], v168 offset:33792
	ds_read_b128 v[194:197], v168 offset:34816
	ds_read_b128 v[204:207], v168 offset:35840
	ds_read_b128 v[208:211], v168 offset:36864
	ds_read_b128 v[212:215], v168 offset:37888
	ds_read_b128 v[216:219], v168 offset:38912
	ds_read_b128 v[220:223], v168 offset:39936
	global_load_lds_dwordx4 v[228:229], off
	v_lshl_add_u64 v[228:229], s[26:27], 0, v[148:149]
	s_mov_b32 m0, s63
	s_nop 0
	global_load_lds_dwordx4 v[228:229], off
	s_waitcnt vmcnt(8)
	s_waitcnt lgkmcnt(0)
	s_barrier
	s_setprio 1
	s_waitcnt lgkmcnt(0)
	v_mfma_f32_16x16x32_bf16 v[128:131], v[132:135], v[186:189], v[128:131]
	v_mfma_f32_16x16x32_bf16 v[128:131], v[136:139], v[190:193], v[128:131]
	v_mfma_f32_16x16x32_bf16 v[124:127], v[140:143], v[186:189], v[124:127]
	v_mfma_f32_16x16x32_bf16 v[124:127], v[144:147], v[190:193], v[124:127]
	v_mfma_f32_16x16x32_bf16 v[116:119], v[132:135], v[194:197], v[116:119]
	v_mfma_f32_16x16x32_bf16 v[116:119], v[136:139], v[204:207], v[116:119]
	v_mfma_f32_16x16x32_bf16 v[112:115], v[140:143], v[194:197], v[112:115]
	v_mfma_f32_16x16x32_bf16 v[112:115], v[144:147], v[204:207], v[112:115]
	v_mfma_f32_16x16x32_bf16 v[104:107], v[132:135], v[208:211], v[104:107]
	v_mfma_f32_16x16x32_bf16 v[104:107], v[136:139], v[212:215], v[104:107]
	v_mfma_f32_16x16x32_bf16 v[96:99], v[140:143], v[208:211], v[96:99]
	v_mfma_f32_16x16x32_bf16 v[96:99], v[144:147], v[212:215], v[96:99]
	v_mfma_f32_16x16x32_bf16 v[88:91], v[132:135], v[216:219], v[88:91]
	v_mfma_f32_16x16x32_bf16 v[88:91], v[136:139], v[220:223], v[88:91]
	v_mfma_f32_16x16x32_bf16 v[80:83], v[140:143], v[216:219], v[80:83]
	v_mfma_f32_16x16x32_bf16 v[80:83], v[144:147], v[220:223], v[80:83]
	s_setprio 0
	s_setprio 1
	v_mfma_f32_16x16x32_bf16 v[120:123], v[170:173], v[186:189], v[120:123]
	v_mfma_f32_16x16x32_bf16 v[120:123], v[174:177], v[190:193], v[120:123]
	v_mfma_f32_16x16x32_bf16 v[108:111], v[178:181], v[186:189], v[108:111]
	v_mfma_f32_16x16x32_bf16 v[108:111], v[182:185], v[190:193], v[108:111]
	v_mfma_f32_16x16x32_bf16 v[100:103], v[170:173], v[194:197], v[100:103]
	v_mfma_f32_16x16x32_bf16 v[100:103], v[174:177], v[204:207], v[100:103]
	v_mfma_f32_16x16x32_bf16 v[92:95], v[178:181], v[194:197], v[92:95]
	v_mfma_f32_16x16x32_bf16 v[92:95], v[182:185], v[204:207], v[92:95]
	v_mfma_f32_16x16x32_bf16 v[84:87], v[170:173], v[208:211], v[84:87]
	v_mfma_f32_16x16x32_bf16 v[84:87], v[174:177], v[212:215], v[84:87]
	v_mfma_f32_16x16x32_bf16 v[76:79], v[178:181], v[208:211], v[76:79]
	v_mfma_f32_16x16x32_bf16 v[76:79], v[182:185], v[212:215], v[76:79]
	v_mfma_f32_16x16x32_bf16 v[72:75], v[170:173], v[216:219], v[72:75]
	v_mfma_f32_16x16x32_bf16 v[72:75], v[174:177], v[220:223], v[72:75]
	s_setprio 2
	s_barrier
; #define PG8_STAGE(bufoff, gbase, voff) do { _Pragma("unroll") for (int _i = 0; _i < 2; ++_i) \
;         __builtin_amdgcn_global_load_lds((const unsigned*)((const char*)(gbase) + (voff)[_i]), (LAS unsigned*)(lds + (bufoff) + ldsw + _i * 8192), 16, 0, 0); } while (0)
; #define PG8_LDA(dst, b, h) do { _Pragma("unroll") for (int m = 0; m < 4; ++m) _Pragma("unroll") for (int k = 0; k < 2; ++k) dst[m][k] = *(const LAS bf16x8*)(lds + PG8_SA(b, h) + aoff + m * 2048 + k * 1024); } while (0)
; #define PG8_LDB(dst, b, h) do { _Pragma("unroll") for (int n = 0; n < 2; ++n) _Pragma("unroll") for (int k = 0; k < 2; ++k) dst[n][k] = *(const LAS bf16x8*)(lds + PG8_SB(b, h) + boff + n * 2048 + k * 1024); } while (0)
; #define PG8_WAIT_V(n) asm volatile("s_waitcnt vmcnt(" #n ")" ::: "memory")
; #define PG8_BAR __builtin_amdgcn_s_barrier()
; template <class Epi, class Sched, bool ALIGN_EPI = true>
; __device__ __forceinline__ void gemm_phase(LAS unsigned char* lds, const Gemm g, const Sched& S, const Epi& E) {
;     ...
;         for (int t = 0; t < nt; t += 2) {
;             const bool last = (t == nt - 2);
;             const char* a1 = cA + (size_t)(t + 1) * kstep;
;             const char* a2 = last ? nA : cA + (size_t)(t + 2) * kstep; const char* b2 = last ? nB : cB + (size_t)(t + 2) * kstep;
;             const char* a3 = a2 + kstep; const char* b3 = b2 + kstep;
;             PG8_LDB(B0, 0, 0); PG8_LDB(B1, 0, 1); PG8_SCHED; PG8_LDA(At, 0, 0); PG8_STAGE(PG8_SA(1, 1), a1 + hA, voffA);
;             PG8_WAIT_V(8); PG8_WAIT_L(0); PG8_BAR; PG8_MMA(0, 0, At, B0); PG8_MMA(0, 1, At, B1); PG8_BAR; PG8_SCHED;
;             PG8_LDA(At, 0, 1); PG8_STAGE(PG8_SB(0, 0), b2, voffB); PG8_STAGE(PG8_SB(0, 1), b2 + hB, voffB); PG8_STAGE(PG8_SA(0, 0), a2, voffA);
;             PG8_WAIT_V(8); PG8_WAIT_L(0); PG8_BAR; PG8_MMA(1, 0, At, B0); PG8_MMA(1, 1, At, B1); PG8_BAR; PG8_SCHED;
;             PG8_LDB(B0, 1, 0); PG8_LDB(B1, 1, 1); PG8_SCHED; PG8_LDA(At, 1, 0); PG8_STAGE(PG8_SA(0, 1), a2 + hA, voffA);
;             PG8_WAIT_V(8); PG8_WAIT_L(0); PG8_BAR; PG8_MMA(0, 0, At, B0); PG8_MMA(0, 1, At, B1); PG8_BAR; PG8_SCHED;
;             PG8_LDA(At, 1, 1); PG8_STAGE(PG8_SB(1, 0), b3, voffB); PG8_STAGE(PG8_SB(1, 1), b3 + hB, voffB); PG8_STAGE(PG8_SA(1, 0), a3, voffA);
;             PG8_WAIT_V(8); PG8_WAIT_L(0); PG8_BAR; PG8_MMA(1, 0, At, B0); PG8_MMA(1, 1, At, B1); PG8_BAR; PG8_SCHED;
	v_mfma_f32_16x16x32_bf16 v[68:71], v[178:181], v[216:219], v[68:71]
	v_mfma_f32_16x16x32_bf16 v[68:71], v[182:185], v[220:223], v[68:71]
	s_setprio 0
	s_add_i32 s26, s30, s59
	v_lshl_add_u64 v[156:157], v[156:157], 0, s[86:87]
	s_mov_b32 m0, s26
	ds_read_b128 v[186:189], v168 offset:49152
	ds_read_b128 v[190:193], v168 offset:50176
	ds_read_b128 v[194:197], v168 offset:51200
	ds_read_b128 v[204:207], v168 offset:52224
	ds_read_b128 v[208:211], v168 offset:53248
	ds_read_b128 v[212:215], v168 offset:54272
	ds_read_b128 v[216:219], v168 offset:55296
	ds_read_b128 v[220:223], v168 offset:56320
	global_load_lds_dwordx4 v[156:157], off
	s_add_i32 m0, s26, 0x2000
	s_add_u32 s26, s42, 0x80080
	v_lshl_add_u64 v[156:157], v[164:165], 0, s[86:87]
	s_addc_u32 s27, s43, 0
	s_add_i32 s30, s31, s59
	global_load_lds_dwordx4 v[156:157], off
	v_lshl_add_u64 v[156:157], s[26:27], 0, v[2:3]
	s_mov_b32 m0, s30
	s_nop 0
	global_load_lds_dwordx4 v[156:157], off
	v_lshl_add_u64 v[156:157], s[26:27], 0, v[0:1]
	s_add_i32 m0, s30, 0x2000
	s_nop 0
	global_load_lds_dwordx4 v[156:157], off
	v_lshl_add_u64 v[156:157], v[224:225], 0, s[86:87]
	s_mov_b32 m0, s64
	s_nop 0
	global_load_lds_dwordx4 v[156:157], off
	v_lshl_add_u64 v[156:157], v[226:227], 0, s[86:87]
	s_mov_b32 m0, s65
	s_nop 0
	global_load_lds_dwordx4 v[156:157], off
	s_add_i32 s25, s25, 2
	s_add_u32 s6, s6, 0x100
	s_addc_u32 s7, s7, 0
	s_add_u32 s19, s19, 0x100
	s_addc_u32 s24, s24, 0
	s_add_u32 s26, s6, 0xfff80080
	s_addc_u32 s27, s7, -1
	s_add_i32 s30, 0, 0x10000
	s_cmp_eq_u32 s25, 28
	s_cselect_b32 s45, s15, s27
	s_cselect_b32 s44, s17, s26
	s_cselect_b32 s43, s13, s24
	s_cselect_b32 s42, s18, s19
	s_add_i32 s31, 0, 0x14000
	s_waitcnt vmcnt(8)
	s_waitcnt lgkmcnt(0)
	s_barrier
	s_setprio 1
	s_waitcnt lgkmcnt(0)
	v_mfma_f32_16x16x32_bf16 v[64:67], v[132:135], v[186:189], v[64:67]
	v_mfma_f32_16x16x32_bf16 v[64:67], v[136:139], v[190:193], v[64:67]
	v_mfma_f32_16x16x32_bf16 v[60:63], v[140:143], v[186:189], v[60:63]
	v_mfma_f32_16x16x32_bf16 v[60:63], v[144:147], v[190:193], v[60:63]
	v_mfma_f32_16x16x32_bf16 v[56:59], v[132:135], v[194:197], v[56:59]
	v_mfma_f32_16x16x32_bf16 v[56:59], v[136:139], v[204:207], v[56:59]
	v_mfma_f32_16x16x32_bf16 v[48:51], v[140:143], v[194:197], v[48:51]
	v_mfma_f32_16x16x32_bf16 v[48:51], v[144:147], v[204:207], v[48:51]
	v_mfma_f32_16x16x32_bf16 v[40:43], v[132:135], v[208:211], v[40:43]
	v_mfma_f32_16x16x32_bf16 v[40:43], v[136:139], v[212:215], v[40:43]
	v_mfma_f32_16x16x32_bf16 v[32:35], v[140:143], v[208:211], v[32:35]
	v_mfma_f32_16x16x32_bf16 v[32:35], v[144:147], v[212:215], v[32:35]
	v_mfma_f32_16x16x32_bf16 v[24:27], v[132:135], v[216:219], v[24:27]
	v_mfma_f32_16x16x32_bf16 v[24:27], v[136:139], v[220:223], v[24:27]
	v_mfma_f32_16x16x32_bf16 v[16:19], v[140:143], v[216:219], v[16:19]
	v_mfma_f32_16x16x32_bf16 v[16:19], v[144:147], v[220:223], v[16:19]
	s_setprio 0
	s_setprio 1
	v_mfma_f32_16x16x32_bf16 v[52:55], v[170:173], v[186:189], v[52:55]
	v_mfma_f32_16x16x32_bf16 v[52:55], v[174:177], v[190:193], v[52:55]
	v_mfma_f32_16x16x32_bf16 v[44:47], v[178:181], v[186:189], v[44:47]
	v_mfma_f32_16x16x32_bf16 v[44:47], v[182:185], v[190:193], v[44:47]
	v_mfma_f32_16x16x32_bf16 v[36:39], v[170:173], v[194:197], v[36:39]
	v_mfma_f32_16x16x32_bf16 v[36:39], v[174:177], v[204:207], v[36:39]
	v_mfma_f32_16x16x32_bf16 v[28:31], v[178:181], v[194:197], v[28:31]
	v_mfma_f32_16x16x32_bf16 v[28:31], v[182:185], v[204:207], v[28:31]
	v_mfma_f32_16x16x32_bf16 v[20:23], v[170:173], v[208:211], v[20:23]
	v_mfma_f32_16x16x32_bf16 v[20:23], v[174:177], v[212:215], v[20:23]
	v_mfma_f32_16x16x32_bf16 v[12:15], v[178:181], v[208:211], v[12:15]
	v_mfma_f32_16x16x32_bf16 v[12:15], v[182:185], v[212:215], v[12:15]
	v_mfma_f32_16x16x32_bf16 v[8:11], v[170:173], v[216:219], v[8:11]
	v_mfma_f32_16x16x32_bf16 v[8:11], v[174:177], v[220:223], v[8:11]
	s_setprio 2
	s_barrier
	v_mfma_f32_16x16x32_bf16 v[4:7], v[178:181], v[216:219], v[4:7]
	v_mfma_f32_16x16x32_bf16 v[4:7], v[182:185], v[220:223], v[4:7]
	s_setprio 0
	s_cmp_gt_u32 s25, 29
	s_cbranch_scc1 .Lpeel_exit_77
.LBB0_77:
	v_add_u32_e32 v144, s30, v166
	v_add_u32_e32 v156, s31, v166
	ds_read_b128 v[132:135], v144
	ds_read_b128 v[136:139], v144 offset:1024
	ds_read_b128 v[140:143], v144 offset:2048
	ds_read_b128 v[144:147], v144 offset:3072
	ds_read_b128 v[170:173], v156
	ds_read_b128 v[174:177], v156 offset:1024
	ds_read_b128 v[178:181], v156 offset:2048
	ds_read_b128 v[182:185], v156 offset:3072
	v_lshl_add_u64 v[156:157], s[6:7], 0, v[152:153]
	s_add_i32 m0, s60, 0xc000
	ds_read_b128 v[186:189], v168
	ds_read_b128 v[190:193], v168 offset:1024
	ds_read_b128 v[194:197], v168 offset:2048
	ds_read_b128 v[204:207], v168 offset:3072
	ds_read_b128 v[208:211], v168 offset:4096
	ds_read_b128 v[212:215], v168 offset:5120
	ds_read_b128 v[216:219], v168 offset:6144
	ds_read_b128 v[220:223], v168 offset:7168
	global_load_lds_dwordx4 v[156:157], off
	v_lshl_add_u64 v[156:157], s[6:7], 0, v[154:155]
	s_add_i32 m0, s60, 0xe000
	s_nop 0
	global_load_lds_dwordx4 v[156:157], off
	s_waitcnt vmcnt(8)
	s_waitcnt lgkmcnt(0)
	s_barrier
; #define PG8_STAGE(bufoff, gbase, voff) do { _Pragma("unroll") for (int _i = 0; _i < 2; ++_i) \
;         __builtin_amdgcn_global_load_lds((const unsigned*)((const char*)(gbase) + (voff)[_i]), (LAS unsigned*)(lds + (bufoff) + ldsw + _i * 8192), 16, 0, 0); } while (0)
; #define PG8_LDA(dst, b, h) do { _Pragma("unroll") for (int m = 0; m < 4; ++m) _Pragma("unroll") for (int k = 0; k < 2; ++k) dst[m][k] = *(const LAS bf16x8*)(lds + PG8_SA(b, h) + aoff + m * 2048 + k * 1024); } while (0)
; #define PG8_LDB(dst, b, h) do { _Pragma("unroll") for (int n = 0; n < 2; ++n) _Pragma("unroll") for (int k = 0; k < 2; ++k) dst[n][k] = *(const LAS bf16x8*)(lds + PG8_SB(b, h) + boff + n * 2048 + k * 1024); } while (0)
; #define PG8_MMA(ai, bj, At, Bt) do { __builtin_amdgcn_s_setprio(1); _Pragma("unroll") for (int m = 0; m < 4; ++m) _Pragma("unroll") for (int n = 0; n < 2; ++n) _Pragma("unroll") for (int k = 0; k < 2; ++k) \
;         acc[ai][bj][m][n] = __builtin_amdgcn_mfma_f32_16x16x32_bf16(Bt[n][k], At[m][k], acc[ai][bj][m][n], 0, 0, 0); __builtin_amdgcn_s_setprio(0); } while (0)
; #define PG8_WAIT_V(n) asm volatile("s_waitcnt vmcnt(" #n ")" ::: "memory")
; #define PG8_BAR __builtin_amdgcn_s_barrier()
; template <class Epi, class Sched, bool ALIGN_EPI = true>
; __device__ __forceinline__ void gemm_phase(LAS unsigned char* lds, const Gemm g, const Sched& S, const Epi& E) {
;     ...
;             PG8_LDB(B0, 0, 0); PG8_LDB(B1, 0, 1); PG8_SCHED; PG8_LDA(At, 0, 0); PG8_STAGE(PG8_SA(1, 1), a1 + hA, voffA);
;             PG8_WAIT_V(8); PG8_WAIT_L(0); PG8_BAR; PG8_MMA(0, 0, At, B0); PG8_MMA(0, 1, At, B1); PG8_BAR; PG8_SCHED;
;             PG8_LDA(At, 0, 1); PG8_STAGE(PG8_SB(0, 0), b2, voffB); PG8_STAGE(PG8_SB(0, 1), b2 + hB, voffB); PG8_STAGE(PG8_SA(0, 0), a2, voffA);
;             PG8_WAIT_V(8); PG8_WAIT_L(0); PG8_BAR; PG8_MMA(1, 0, At, B0); PG8_MMA(1, 1, At, B1); PG8_BAR; PG8_SCHED;
;             PG8_LDB(B0, 1, 0); PG8_LDB(B1, 1, 1); PG8_SCHED; PG8_LDA(At, 1, 0); PG8_STAGE(PG8_SA(0, 1), a2 + hA, voffA);
;             PG8_WAIT_V(8); PG8_WAIT_L(0); PG8_BAR; PG8_MMA(0, 0, At, B0); PG8_MMA(0, 1, At, B1); PG8_BAR; PG8_SCHED;
;             PG8_LDA(At, 1, 1); PG8_STAGE(PG8_SB(1, 0), b3, voffB); PG8_STAGE(PG8_SB(1, 1), b3 + hB, voffB); PG8_STAGE(PG8_SA(1, 0), a3, voffA);
;             PG8_WAIT_V(8); PG8_WAIT_L(0); PG8_BAR; PG8_MMA(1, 0, At, B0); PG8_MMA(1, 1, At, B1); PG8_BAR; PG8_SCHED;
	s_setprio 1
	s_waitcnt lgkmcnt(0)
	v_mfma_f32_16x16x32_bf16 v[128:131], v[132:135], v[186:189], v[128:131]
	v_mfma_f32_16x16x32_bf16 v[128:131], v[136:139], v[190:193], v[128:131]
	v_mfma_f32_16x16x32_bf16 v[124:127], v[140:143], v[186:189], v[124:127]
	v_mfma_f32_16x16x32_bf16 v[124:127], v[144:147], v[190:193], v[124:127]
	v_mfma_f32_16x16x32_bf16 v[116:119], v[132:135], v[194:197], v[116:119]
	v_mfma_f32_16x16x32_bf16 v[116:119], v[136:139], v[204:207], v[116:119]
	v_mfma_f32_16x16x32_bf16 v[112:115], v[140:143], v[194:197], v[112:115]
	v_mfma_f32_16x16x32_bf16 v[112:115], v[144:147], v[204:207], v[112:115]
	v_mfma_f32_16x16x32_bf16 v[104:107], v[132:135], v[208:211], v[104:107]
	v_mfma_f32_16x16x32_bf16 v[104:107], v[136:139], v[212:215], v[104:107]
	v_mfma_f32_16x16x32_bf16 v[96:99], v[140:143], v[208:211], v[96:99]
	v_mfma_f32_16x16x32_bf16 v[96:99], v[144:147], v[212:215], v[96:99]
	v_mfma_f32_16x16x32_bf16 v[88:91], v[132:135], v[216:219], v[88:91]
	v_mfma_f32_16x16x32_bf16 v[88:91], v[136:139], v[220:223], v[88:91]
	v_mfma_f32_16x16x32_bf16 v[80:83], v[140:143], v[216:219], v[80:83]
	v_mfma_f32_16x16x32_bf16 v[80:83], v[144:147], v[220:223], v[80:83]
	s_setprio 0
	s_setprio 1
	v_mfma_f32_16x16x32_bf16 v[120:123], v[170:173], v[186:189], v[120:123]
	v_mfma_f32_16x16x32_bf16 v[120:123], v[174:177], v[190:193], v[120:123]
	v_mfma_f32_16x16x32_bf16 v[108:111], v[178:181], v[186:189], v[108:111]
	v_mfma_f32_16x16x32_bf16 v[108:111], v[182:185], v[190:193], v[108:111]
	v_mfma_f32_16x16x32_bf16 v[100:103], v[170:173], v[194:197], v[100:103]
	v_mfma_f32_16x16x32_bf16 v[100:103], v[174:177], v[204:207], v[100:103]
	v_mfma_f32_16x16x32_bf16 v[92:95], v[178:181], v[194:197], v[92:95]
	v_mfma_f32_16x16x32_bf16 v[92:95], v[182:185], v[204:207], v[92:95]
	v_mfma_f32_16x16x32_bf16 v[84:87], v[170:173], v[208:211], v[84:87]
	v_mfma_f32_16x16x32_bf16 v[84:87], v[174:177], v[212:215], v[84:87]
	v_mfma_f32_16x16x32_bf16 v[76:79], v[178:181], v[208:211], v[76:79]
	v_mfma_f32_16x16x32_bf16 v[76:79], v[182:185], v[212:215], v[76:79]
	v_mfma_f32_16x16x32_bf16 v[72:75], v[170:173], v[216:219], v[72:75]
	v_mfma_f32_16x16x32_bf16 v[72:75], v[174:177], v[220:223], v[72:75]
	s_setprio 2
	s_barrier
	v_mfma_f32_16x16x32_bf16 v[68:71], v[178:181], v[216:219], v[68:71]
	v_mfma_f32_16x16x32_bf16 v[68:71], v[182:185], v[220:223], v[68:71]
	s_setprio 0
	s_add_i32 s26, s30, s59
	v_lshl_add_u64 v[156:157], s[42:43], 0, v[2:3]
	s_mov_b32 m0, s26
	ds_read_b128 v[186:189], v168 offset:16384
	ds_read_b128 v[190:193], v168 offset:17408
	ds_read_b128 v[194:197], v168 offset:18432
	ds_read_b128 v[204:207], v168 offset:19456
	ds_read_b128 v[208:211], v168 offset:20480
	ds_read_b128 v[212:215], v168 offset:21504
	ds_read_b128 v[216:219], v168 offset:22528
	ds_read_b128 v[220:223], v168 offset:23552
	global_load_lds_dwordx4 v[156:157], off
	s_add_i32 m0, s26, 0x2000
	s_add_u32 s26, s42, 0x80000
	v_lshl_add_u64 v[164:165], s[42:43], 0, v[0:1]
	s_addc_u32 s27, s43, 0
	s_add_i32 s30, s31, s59
	global_load_lds_dwordx4 v[164:165], off
	v_lshl_add_u64 v[224:225], s[26:27], 0, v[2:3]
	s_mov_b32 m0, s30
	v_lshl_add_u64 v[226:227], s[44:45], 0, v[148:149]
	global_load_lds_dwordx4 v[224:225], off
	v_lshl_add_u64 v[224:225], s[26:27], 0, v[0:1]
	s_add_i32 m0, s30, 0x2000
	s_nop 0
	global_load_lds_dwordx4 v[224:225], off
	v_lshl_add_u64 v[224:225], s[44:45], 0, v[150:151]
	s_mov_b32 m0, s60
	s_nop 0
	global_load_lds_dwordx4 v[224:225], off
	s_mov_b32 m0, s61
	s_nop 0
	global_load_lds_dwordx4 v[226:227], off
	s_waitcnt vmcnt(8)
	s_waitcnt lgkmcnt(0)
	s_barrier
	s_setprio 1
	s_waitcnt lgkmcnt(0)
	v_mfma_f32_16x16x32_bf16 v[64:67], v[132:135], v[186:189], v[64:67]
	v_mfma_f32_16x16x32_bf16 v[64:67], v[136:139], v[190:193], v[64:67]
	v_mfma_f32_16x16x32_bf16 v[60:63], v[140:143], v[186:189], v[60:63]
	v_mfma_f32_16x16x32_bf16 v[60:63], v[144:147], v[190:193], v[60:63]
	v_mfma_f32_16x16x32_bf16 v[56:59], v[132:135], v[194:197], v[56:59]
	v_mfma_f32_16x16x32_bf16 v[56:59], v[136:139], v[204:207], v[56:59]
	v_mfma_f32_16x16x32_bf16 v[48:51], v[140:143], v[194:197], v[48:51]
	v_mfma_f32_16x16x32_bf16 v[48:51], v[144:147], v[204:207], v[48:51]
	v_mfma_f32_16x16x32_bf16 v[40:43], v[132:135], v[208:211], v[40:43]
	v_mfma_f32_16x16x32_bf16 v[40:43], v[136:139], v[212:215], v[40:43]
	v_mfma_f32_16x16x32_bf16 v[32:35], v[140:143], v[208:211], v[32:35]
	v_mfma_f32_16x16x32_bf16 v[32:35], v[144:147], v[212:215], v[32:35]
	v_mfma_f32_16x16x32_bf16 v[24:27], v[132:135], v[216:219], v[24:27]
	v_mfma_f32_16x16x32_bf16 v[24:27], v[136:139], v[220:223], v[24:27]
	v_mfma_f32_16x16x32_bf16 v[16:19], v[140:143], v[216:219], v[16:19]
	v_mfma_f32_16x16x32_bf16 v[16:19], v[144:147], v[220:223], v[16:19]
	s_setprio 0
	s_setprio 1
	v_mfma_f32_16x16x32_bf16 v[52:55], v[170:173], v[186:189], v[52:55]
	v_mfma_f32_16x16x32_bf16 v[52:55], v[174:177], v[190:193], v[52:55]
	v_mfma_f32_16x16x32_bf16 v[44:47], v[178:181], v[186:189], v[44:47]
	v_mfma_f32_16x16x32_bf16 v[44:47], v[182:185], v[190:193], v[44:47]
	v_mfma_f32_16x16x32_bf16 v[36:39], v[170:173], v[194:197], v[36:39]
	v_mfma_f32_16x16x32_bf16 v[36:39], v[174:177], v[204:207], v[36:39]
	v_mfma_f32_16x16x32_bf16 v[28:31], v[178:181], v[194:197], v[28:31]
	v_mfma_f32_16x16x32_bf16 v[28:31], v[182:185], v[204:207], v[28:31]
	v_mfma_f32_16x16x32_bf16 v[20:23], v[170:173], v[208:211], v[20:23]
	v_mfma_f32_16x16x32_bf16 v[20:23], v[174:177], v[212:215], v[20:23]
	v_mfma_f32_16x16x32_bf16 v[12:15], v[178:181], v[208:211], v[12:15]
	v_mfma_f32_16x16x32_bf16 v[12:15], v[182:185], v[212:215], v[12:15]
	v_mfma_f32_16x16x32_bf16 v[8:11], v[170:173], v[216:219], v[8:11]
	v_mfma_f32_16x16x32_bf16 v[8:11], v[174:177], v[220:223], v[8:11]
	s_setprio 2
	s_barrier
; #define PG8_STAGE(bufoff, gbase, voff) do { _Pragma("unroll") for (int _i = 0; _i < 2; ++_i) \
;         __builtin_amdgcn_global_load_lds((const unsigned*)((const char*)(gbase) + (voff)[_i]), (LAS unsigned*)(lds + (bufoff) + ldsw + _i * 8192), 16, 0, 0); } while (0)
; #define PG8_LDA(dst, b, h) do { _Pragma("unroll") for (int m = 0; m < 4; ++m) _Pragma("unroll") for (int k = 0; k < 2; ++k) dst[m][k] = *(const LAS bf16x8*)(lds + PG8_SA(b, h) + aoff + m * 2048 + k * 1024); } while (0)
; #define PG8_LDB(dst, b, h) do { _Pragma("unroll") for (int n = 0; n < 2; ++n) _Pragma("unroll") for (int k = 0; k < 2; ++k) dst[n][k] = *(const LAS bf16x8*)(lds + PG8_SB(b, h) + boff + n * 2048 + k * 1024); } while (0)
; #define PG8_MMA(ai, bj, At, Bt) do { __builtin_amdgcn_s_setprio(1); _Pragma("unroll") for (int m = 0; m < 4; ++m) _Pragma("unroll") for (int n = 0; n < 2; ++n) _Pragma("unroll") for (int k = 0; k < 2; ++k) \
;         acc[ai][bj][m][n] = __builtin_amdgcn_mfma_f32_16x16x32_bf16(Bt[n][k], At[m][k], acc[ai][bj][m][n], 0, 0, 0); __builtin_amdgcn_s_setprio(0); } while (0)
; #define PG8_WAIT_V(n) asm volatile("s_waitcnt vmcnt(" #n ")" ::: "memory")
; #define PG8_WAIT_L(n) asm volatile("s_waitcnt lgkmcnt(" #n ")" ::: "memory")
; #define PG8_BAR __builtin_amdgcn_s_barrier()
; #define PG8_SCHED __builtin_amdgcn_sched_barrier(0)
; template <class Epi, class Sched, bool ALIGN_EPI = true>
; __device__ __forceinline__ void gemm_phase(LAS unsigned char* lds, const Gemm g, const Sched& S, const Epi& E) {
;     ...
;             PG8_LDB(B0, 1, 0); PG8_LDB(B1, 1, 1); PG8_SCHED; PG8_LDA(At, 1, 0); PG8_STAGE(PG8_SA(0, 1), a2 + hA, voffA);
;             PG8_WAIT_V(8); PG8_WAIT_L(0); PG8_BAR; PG8_MMA(0, 0, At, B0); PG8_MMA(0, 1, At, B1); PG8_BAR; PG8_SCHED;
;             PG8_LDA(At, 1, 1); PG8_STAGE(PG8_SB(1, 0), b3, voffB); PG8_STAGE(PG8_SB(1, 1), b3 + hB, voffB); PG8_STAGE(PG8_SA(1, 0), a3, voffA);
;             PG8_WAIT_V(8); PG8_WAIT_L(0); PG8_BAR; PG8_MMA(1, 0, At, B0); PG8_MMA(1, 1, At, B1); PG8_BAR; PG8_SCHED;
	v_mfma_f32_16x16x32_bf16 v[4:7], v[178:181], v[216:219], v[4:7]
	v_mfma_f32_16x16x32_bf16 v[4:7], v[182:185], v[220:223], v[4:7]
	s_setprio 0
	s_add_i32 s30, 0, 0x18000
	s_add_i32 s31, 0, 0x1c000
	v_add_u32_e32 v144, s30, v166
	v_add_u32_e32 v160, s31, v166
	ds_read_b128 v[132:135], v144
	ds_read_b128 v[136:139], v144 offset:1024
	ds_read_b128 v[140:143], v144 offset:2048
	ds_read_b128 v[144:147], v144 offset:3072
	ds_read_b128 v[170:173], v160
	ds_read_b128 v[174:177], v160 offset:1024
	ds_read_b128 v[178:181], v160 offset:2048
	ds_read_b128 v[182:185], v160 offset:3072
	s_add_u32 s26, s44, 0x80000
	s_addc_u32 s27, s45, 0
	s_mov_b32 m0, s62
	v_lshl_add_u64 v[228:229], s[26:27], 0, v[150:151]
	ds_read_b128 v[186:189], v168 offset:32768
	ds_read_b128 v[190:193], v168 offset:33792
	ds_read_b128 v[194:197], v168 offset:34816
	ds_read_b128 v[204:207], v168 offset:35840
	ds_read_b128 v[208:211], v168 offset:36864
	ds_read_b128 v[212:215], v168 offset:37888
	ds_read_b128 v[216:219], v168 offset:38912
	ds_read_b128 v[220:223], v168 offset:39936
	global_load_lds_dwordx4 v[228:229], off
	v_lshl_add_u64 v[228:229], s[26:27], 0, v[148:149]
	s_mov_b32 m0, s63
	s_nop 0
	global_load_lds_dwordx4 v[228:229], off
	s_waitcnt vmcnt(8)
	s_waitcnt lgkmcnt(0)
	s_barrier
	s_setprio 1
	s_waitcnt lgkmcnt(0)
	v_mfma_f32_16x16x32_bf16 v[128:131], v[132:135], v[186:189], v[128:131]
	v_mfma_f32_16x16x32_bf16 v[128:131], v[136:139], v[190:193], v[128:131]
	v_mfma_f32_16x16x32_bf16 v[124:127], v[140:143], v[186:189], v[124:127]
	v_mfma_f32_16x16x32_bf16 v[124:127], v[144:147], v[190:193], v[124:127]
	v_mfma_f32_16x16x32_bf16 v[116:119], v[132:135], v[194:197], v[116:119]
	v_mfma_f32_16x16x32_bf16 v[116:119], v[136:139], v[204:207], v[116:119]
	v_mfma_f32_16x16x32_bf16 v[112:115], v[140:143], v[194:197], v[112:115]
	v_mfma_f32_16x16x32_bf16 v[112:115], v[144:147], v[204:207], v[112:115]
	v_mfma_f32_16x16x32_bf16 v[104:107], v[132:135], v[208:211], v[104:107]
	v_mfma_f32_16x16x32_bf16 v[104:107], v[136:139], v[212:215], v[104:107]
	v_mfma_f32_16x16x32_bf16 v[96:99], v[140:143], v[208:211], v[96:99]
	v_mfma_f32_16x16x32_bf16 v[96:99], v[144:147], v[212:215], v[96:99]
	v_mfma_f32_16x16x32_bf16 v[88:91], v[132:135], v[216:219], v[88:91]
	v_mfma_f32_16x16x32_bf16 v[88:91], v[136:139], v[220:223], v[88:91]
	v_mfma_f32_16x16x32_bf16 v[80:83], v[140:143], v[216:219], v[80:83]
	v_mfma_f32_16x16x32_bf16 v[80:83], v[144:147], v[220:223], v[80:83]
	s_setprio 0
	s_setprio 1
	v_mfma_f32_16x16x32_bf16 v[120:123], v[170:173], v[186:189], v[120:123]
	v_mfma_f32_16x16x32_bf16 v[120:123], v[174:177], v[190:193], v[120:123]
	v_mfma_f32_16x16x32_bf16 v[108:111], v[178:181], v[186:189], v[108:111]
	v_mfma_f32_16x16x32_bf16 v[108:111], v[182:185], v[190:193], v[108:111]
	v_mfma_f32_16x16x32_bf16 v[100:103], v[170:173], v[194:197], v[100:103]
	v_mfma_f32_16x16x32_bf16 v[100:103], v[174:177], v[204:207], v[100:103]
	v_mfma_f32_16x16x32_bf16 v[92:95], v[178:181], v[194:197], v[92:95]
	v_mfma_f32_16x16x32_bf16 v[92:95], v[182:185], v[204:207], v[92:95]
	v_mfma_f32_16x16x32_bf16 v[84:87], v[170:173], v[208:211], v[84:87]
	v_mfma_f32_16x16x32_bf16 v[84:87], v[174:177], v[212:215], v[84:87]
	v_mfma_f32_16x16x32_bf16 v[76:79], v[178:181], v[208:211], v[76:79]
	v_mfma_f32_16x16x32_bf16 v[76:79], v[182:185], v[212:215], v[76:79]
	v_mfma_f32_16x16x32_bf16 v[72:75], v[170:173], v[216:219], v[72:75]
	v_mfma_f32_16x16x32_bf16 v[72:75], v[174:177], v[220:223], v[72:75]
	s_setprio 2
	s_barrier
; #define PG8_STAGE(bufoff, gbase, voff) do { _Pragma("unroll") for (int _i = 0; _i < 2; ++_i) \
;         __builtin_amdgcn_global_load_lds((const unsigned*)((const char*)(gbase) + (voff)[_i]), (LAS unsigned*)(lds + (bufoff) + ldsw + _i * 8192), 16, 0, 0); } while (0)
; #define PG8_LDA(dst, b, h) do { _Pragma("unroll") for (int m = 0; m < 4; ++m) _Pragma("unroll") for (int k = 0; k < 2; ++k) dst[m][k] = *(const LAS bf16x8*)(lds + PG8_SA(b, h) + aoff + m * 2048 + k * 1024); } while (0)
; #define PG8_LDB(dst, b, h) do { _Pragma("unroll") for (int n = 0; n < 2; ++n) _Pragma("unroll") for (int k = 0; k < 2; ++k) dst[n][k] = *(const LAS bf16x8*)(lds + PG8_SB(b, h) + boff + n * 2048 + k * 1024); } while (0)
; #define PG8_WAIT_V(n) asm volatile("s_waitcnt vmcnt(" #n ")" ::: "memory")
; #define PG8_BAR __builtin_amdgcn_s_barrier()
; template <class Epi, class Sched, bool ALIGN_EPI = true>
; __device__ __forceinline__ void gemm_phase(LAS unsigned char* lds, const Gemm g, const Sched& S, const Epi& E) {
;     ...
;         for (int t = 0; t < nt; t += 2) {
;             const bool last = (t == nt - 2);
;             const char* a1 = cA + (size_t)(t + 1) * kstep;
;             const char* a2 = last ? nA : cA + (size_t)(t + 2) * kstep; const char* b2 = last ? nB : cB + (size_t)(t + 2) * kstep;
;             const char* a3 = a2 + kstep; const char* b3 = b2 + kstep;
;             PG8_LDB(B0, 0, 0); PG8_LDB(B1, 0, 1); PG8_SCHED; PG8_LDA(At, 0, 0); PG8_STAGE(PG8_SA(1, 1), a1 + hA, voffA);
;             PG8_WAIT_V(8); PG8_WAIT_L(0); PG8_BAR; PG8_MMA(0, 0, At, B0); PG8_MMA(0, 1, At, B1); PG8_BAR; PG8_SCHED;
;             PG8_LDA(At, 0, 1); PG8_STAGE(PG8_SB(0, 0), b2, voffB); PG8_STAGE(PG8_SB(0, 1), b2 + hB, voffB); PG8_STAGE(PG8_SA(0, 0), a2, voffA);
;             PG8_WAIT_V(8); PG8_WAIT_L(0); PG8_BAR; PG8_MMA(1, 0, At, B0); PG8_MMA(1, 1, At, B1); PG8_BAR; PG8_SCHED;
;             PG8_LDB(B0, 1, 0); PG8_LDB(B1, 1, 1); PG8_SCHED; PG8_LDA(At, 1, 0); PG8_STAGE(PG8_SA(0, 1), a2 + hA, voffA);
;             PG8_WAIT_V(8); PG8_WAIT_L(0); PG8_BAR; PG8_MMA(0, 0, At, B0); PG8_MMA(0, 1, At, B1); PG8_BAR; PG8_SCHED;
;             PG8_LDA(At, 1, 1); PG8_STAGE(PG8_SB(1, 0), b3, voffB); PG8_STAGE(PG8_SB(1, 1), b3 + hB, voffB); PG8_STAGE(PG8_SA(1, 0), a3, voffA);
;             PG8_WAIT_V(8); PG8_WAIT_L(0); PG8_BAR; PG8_MMA(1, 0, At, B0); PG8_MMA(1, 1, At, B1); PG8_BAR; PG8_SCHED;
	v_mfma_f32_16x16x32_bf16 v[68:71], v[178:181], v[216:219], v[68:71]
	v_mfma_f32_16x16x32_bf16 v[68:71], v[182:185], v[220:223], v[68:71]
	s_setprio 0
	s_add_i32 s26, s30, s59
	v_lshl_add_u64 v[156:157], v[156:157], 0, s[86:87]
	s_mov_b32 m0, s26
	ds_read_b128 v[186:189], v168 offset:49152
	ds_read_b128 v[190:193], v168 offset:50176
	ds_read_b128 v[194:197], v168 offset:51200
	ds_read_b128 v[204:207], v168 offset:52224
	ds_read_b128 v[208:211], v168 offset:53248
	ds_read_b128 v[212:215], v168 offset:54272
	ds_read_b128 v[216:219], v168 offset:55296
	ds_read_b128 v[220:223], v168 offset:56320
	global_load_lds_dwordx4 v[156:157], off
	s_add_i32 m0, s26, 0x2000
	s_add_u32 s26, s42, 0x80080
	v_lshl_add_u64 v[156:157], v[164:165], 0, s[86:87]
	s_addc_u32 s27, s43, 0
	s_add_i32 s30, s31, s59
	global_load_lds_dwordx4 v[156:157], off
	v_lshl_add_u64 v[156:157], s[26:27], 0, v[2:3]
	s_mov_b32 m0, s30
	s_nop 0
	global_load_lds_dwordx4 v[156:157], off
	v_lshl_add_u64 v[156:157], s[26:27], 0, v[0:1]
	s_add_i32 m0, s30, 0x2000
	s_nop 0
	global_load_lds_dwordx4 v[156:157], off
	v_lshl_add_u64 v[156:157], v[224:225], 0, s[86:87]
	s_mov_b32 m0, s64
	s_nop 0
	global_load_lds_dwordx4 v[156:157], off
	v_lshl_add_u64 v[156:157], v[226:227], 0, s[86:87]
	s_mov_b32 m0, s65
	s_nop 0
	global_load_lds_dwordx4 v[156:157], off
	s_add_i32 s25, s25, 2
	s_add_u32 s6, s6, 0x100
	s_addc_u32 s7, s7, 0
	s_add_u32 s19, s19, 0x100
	s_addc_u32 s24, s24, 0
	s_add_u32 s26, s6, 0xfff80080
	s_addc_u32 s27, s7, -1
	s_add_i32 s30, 0, 0x10000
	s_cmp_eq_u32 s25, 28
	s_cselect_b32 s45, s15, s27
	s_cselect_b32 s44, s17, s26
	s_cselect_b32 s43, s13, s24
	s_cselect_b32 s42, s18, s19
	s_add_i32 s31, 0, 0x14000
	s_waitcnt vmcnt(8)
	s_waitcnt lgkmcnt(0)
	s_barrier
	s_setprio 1
	s_waitcnt lgkmcnt(0)
	v_mfma_f32_16x16x32_bf16 v[64:67], v[132:135], v[186:189], v[64:67]
	v_mfma_f32_16x16x32_bf16 v[64:67], v[136:139], v[190:193], v[64:67]
	v_mfma_f32_16x16x32_bf16 v[60:63], v[140:143], v[186:189], v[60:63]
	v_mfma_f32_16x16x32_bf16 v[60:63], v[144:147], v[190:193], v[60:63]
	v_mfma_f32_16x16x32_bf16 v[56:59], v[132:135], v[194:197], v[56:59]
	v_mfma_f32_16x16x32_bf16 v[56:59], v[136:139], v[204:207], v[56:59]
	v_mfma_f32_16x16x32_bf16 v[48:51], v[140:143], v[194:197], v[48:51]
	v_mfma_f32_16x16x32_bf16 v[48:51], v[144:147], v[204:207], v[48:51]
	v_mfma_f32_16x16x32_bf16 v[40:43], v[132:135], v[208:211], v[40:43]
	v_mfma_f32_16x16x32_bf16 v[40:43], v[136:139], v[212:215], v[40:43]
	v_mfma_f32_16x16x32_bf16 v[32:35], v[140:143], v[208:211], v[32:35]
	v_mfma_f32_16x16x32_bf16 v[32:35], v[144:147], v[212:215], v[32:35]
	v_mfma_f32_16x16x32_bf16 v[24:27], v[132:135], v[216:219], v[24:27]
	v_mfma_f32_16x16x32_bf16 v[24:27], v[136:139], v[220:223], v[24:27]
	v_mfma_f32_16x16x32_bf16 v[16:19], v[140:143], v[216:219], v[16:19]
	v_mfma_f32_16x16x32_bf16 v[16:19], v[144:147], v[220:223], v[16:19]
	s_setprio 0
	s_setprio 1
	v_mfma_f32_16x16x32_bf16 v[52:55], v[170:173], v[186:189], v[52:55]
	v_mfma_f32_16x16x32_bf16 v[52:55], v[174:177], v[190:193], v[52:55]
	v_mfma_f32_16x16x32_bf16 v[44:47], v[178:181], v[186:189], v[44:47]
	v_mfma_f32_16x16x32_bf16 v[44:47], v[182:185], v[190:193], v[44:47]
	v_mfma_f32_16x16x32_bf16 v[36:39], v[170:173], v[194:197], v[36:39]
	v_mfma_f32_16x16x32_bf16 v[36:39], v[174:177], v[204:207], v[36:39]
	v_mfma_f32_16x16x32_bf16 v[28:31], v[178:181], v[194:197], v[28:31]
	v_mfma_f32_16x16x32_bf16 v[28:31], v[182:185], v[204:207], v[28:31]
	v_mfma_f32_16x16x32_bf16 v[20:23], v[170:173], v[208:211], v[20:23]
	v_mfma_f32_16x16x32_bf16 v[20:23], v[174:177], v[212:215], v[20:23]
	v_mfma_f32_16x16x32_bf16 v[12:15], v[178:181], v[208:211], v[12:15]
	v_mfma_f32_16x16x32_bf16 v[12:15], v[182:185], v[212:215], v[12:15]
	v_mfma_f32_16x16x32_bf16 v[8:11], v[170:173], v[216:219], v[8:11]
	v_mfma_f32_16x16x32_bf16 v[8:11], v[174:177], v[220:223], v[8:11]
	s_setprio 2
	s_barrier
	v_mfma_f32_16x16x32_bf16 v[4:7], v[178:181], v[216:219], v[4:7]
	v_mfma_f32_16x16x32_bf16 v[4:7], v[182:185], v[220:223], v[4:7]
	s_setprio 0
	s_cmp_gt_u32 s25, 29
	s_cbranch_scc0 .LBB0_77

;     __device__ bool next(int i, Unit& u) const { if (i >= 2) return false; const int x = c & 7, j = c >> 3; u.pm = 32 * i + 4 * x + (j & 3); u.pn = j >> 2; return true; }
; #define PG8_STAGE(bufoff, gbase, voff) do { _Pragma("unroll") for (int _i = 0; _i < 2; ++_i) \
;         __builtin_amdgcn_global_load_lds((const unsigned*)((const char*)(gbase) + (voff)[_i]), (LAS unsigned*)(lds + (bufoff) + ldsw + _i * 8192), 16, 0, 0); } while (0)
; #define PG8_LDA(dst, b, h) do { _Pragma("unroll") for (int m = 0; m < 4; ++m) _Pragma("unroll") for (int k = 0; k < 2; ++k) dst[m][k] = *(const LAS bf16x8*)(lds + PG8_SA(b, h) + aoff + m * 2048 + k * 1024); } while (0)
; #define PG8_LDB(dst, b, h) do { _Pragma("unroll") for (int n = 0; n < 2; ++n) _Pragma("unroll") for (int k = 0; k < 2; ++k) dst[n][k] = *(const LAS bf16x8*)(lds + PG8_SB(b, h) + boff + n * 2048 + k * 1024); } while (0)
; #define PG8_WAIT_V(n) asm volatile("s_waitcnt vmcnt(" #n ")" ::: "memory")
; #define PG8_WAIT_L(n) asm volatile("s_waitcnt lgkmcnt(" #n ")" ::: "memory")
; #define PG8_BAR __builtin_amdgcn_s_barrier()
; template <class Epi, class Sched, bool ALIGN_EPI = true>
; __device__ __forceinline__ void gemm_phase(LAS unsigned char* lds, const Gemm g, const Sched& S, const Epi& E) {
;     ...
;         const bool has_next = S.next(ui + 1, nxt);
;         const char* nA = has_next ? (const char*)g.A + ((size_t)nxt.pm * BM * g.lda + (size_t)nxt.pn * g.a_pn_off) * 2 : cA; const char* nB = has_next ? (const char*)g.Bt + (size_t)nxt.pn * BM * g.ldb * 2 : cB;
;         for (int t = 0; t < nt; t += 2) {
;             const bool last = (t == nt - 2);
;             const char* a1 = cA + (size_t)(t + 1) * kstep;
;             const char* a2 = last ? nA : cA + (size_t)(t + 2) * kstep; const char* b2 = last ? nB : cB + (size_t)(t + 2) * kstep;
;             const char* a3 = a2 + kstep; const char* b3 = b2 + kstep;
;             PG8_LDB(B0, 0, 0); PG8_LDB(B1, 0, 1); PG8_SCHED; PG8_LDA(At, 0, 0); PG8_STAGE(PG8_SA(1, 1), a1 + hA, voffA);
;             PG8_WAIT_V(8); PG8_WAIT_L(0); PG8_BAR; PG8_MMA(0, 0, At, B0); PG8_MMA(0, 1, At, B1); PG8_BAR; PG8_SCHED;
;             PG8_LDA(At, 0, 1); PG8_STAGE(PG8_SB(0, 0), b2, voffB); PG8_STAGE(PG8_SB(0, 1), b2 + hB, voffB); PG8_STAGE(PG8_SA(0, 0), a2, voffA);
;             PG8_WAIT_V(8); PG8_WAIT_L(0); PG8_BAR; PG8_MMA(1, 0, At, B0); PG8_MMA(1, 1, At, B1); PG8_BAR; PG8_SCHED;
.LBB0_217:
	s_ashr_i32 s11, s10, 31
	s_lshl_b64 s[12:13], s[10:11], 20
	s_add_u32 s12, s46, s12
	s_addc_u32 s13, s47, s13
	s_and_b64 s[14:15], s[4:5], exec
	s_cselect_b32 s11, s13, s39
	s_cselect_b32 s18, s12, s38
	s_ashr_i32 s9, s8, 31
	s_lshl_b64 s[14:15], s[8:9], 20
	s_add_u32 s14, s44, s14
	s_addc_u32 s15, s45, s15
	s_and_b64 s[24:25], s[4:5], exec
	s_cselect_b32 s9, s15, s41
	s_cselect_b32 s19, s14, s40
	s_add_u32 s38, s38, 0x80080
	s_addc_u32 s39, s39, 0
	s_add_u32 s24, s40, 0x100
	s_addc_u32 s25, s41, 0
	s_mov_b32 s26, -2
	s_add_u32 s27, s38, 0xfff80080
	s_addc_u32 s30, s39, -1
	s_add_i32 s31, 0, 0x10000
	s_cmp_eq_u32 s26, 28
	s_cselect_b32 s43, s11, s30
	s_cselect_b32 s42, s18, s27
	v_add_u32_e32 v156, s31, v145
	s_cselect_b32 s41, s9, s25
	s_cselect_b32 s40, s19, s24
	s_add_i32 s27, 0, 0x14000
	ds_read_b128 v[140:143], v156
	ds_read_b128 v[148:151], v156 offset:1024
	ds_read_b128 v[152:155], v156 offset:2048
	ds_read_b128 v[164:167], v156 offset:3072
	v_add_u32_e32 v156, s27, v145
	ds_read_b128 v[168:171], v156
	ds_read_b128 v[172:175], v156 offset:1024
	ds_read_b128 v[176:179], v156 offset:2048
	ds_read_b128 v[180:183], v156 offset:3072
	v_lshl_add_u64 v[156:157], s[38:39], 0, v[136:137]
	s_add_i32 m0, s58, 0xc000
	ds_read_b128 v[184:187], v147
	ds_read_b128 v[188:191], v147 offset:1024
	ds_read_b128 v[192:195], v147 offset:2048
	ds_read_b128 v[204:207], v147 offset:3072
	ds_read_b128 v[208:211], v147 offset:4096
	ds_read_b128 v[212:215], v147 offset:5120
	ds_read_b128 v[216:219], v147 offset:6144
	ds_read_b128 v[220:223], v147 offset:7168
	global_load_lds_dwordx4 v[156:157], off
	v_lshl_add_u64 v[156:157], s[38:39], 0, v[138:139]
	s_add_i32 m0, s58, 0xe000
	s_nop 0
	global_load_lds_dwordx4 v[156:157], off
	s_waitcnt vmcnt(8)
	s_waitcnt lgkmcnt(0)
	s_barrier
	s_setprio 1
	s_waitcnt lgkmcnt(0)
	v_mfma_f32_16x16x32_bf16 v[128:131], v[140:143], v[184:187], 0
	v_mfma_f32_16x16x32_bf16 v[128:131], v[148:151], v[188:191], v[128:131]
	v_mfma_f32_16x16x32_bf16 v[124:127], v[152:155], v[184:187], 0
	v_mfma_f32_16x16x32_bf16 v[124:127], v[164:167], v[188:191], v[124:127]
	v_mfma_f32_16x16x32_bf16 v[120:123], v[140:143], v[192:195], 0
	v_mfma_f32_16x16x32_bf16 v[120:123], v[148:151], v[204:207], v[120:123]
	v_mfma_f32_16x16x32_bf16 v[112:115], v[152:155], v[192:195], 0
	v_mfma_f32_16x16x32_bf16 v[112:115], v[164:167], v[204:207], v[112:115]
	v_mfma_f32_16x16x32_bf16 v[104:107], v[140:143], v[208:211], 0
	v_mfma_f32_16x16x32_bf16 v[104:107], v[148:151], v[212:215], v[104:107]
	v_mfma_f32_16x16x32_bf16 v[96:99], v[152:155], v[208:211], 0
	v_mfma_f32_16x16x32_bf16 v[96:99], v[164:167], v[212:215], v[96:99]
	v_mfma_f32_16x16x32_bf16 v[88:91], v[140:143], v[216:219], 0
	v_mfma_f32_16x16x32_bf16 v[88:91], v[148:151], v[220:223], v[88:91]
	v_mfma_f32_16x16x32_bf16 v[80:83], v[152:155], v[216:219], 0
	v_mfma_f32_16x16x32_bf16 v[80:83], v[164:167], v[220:223], v[80:83]
	s_setprio 0
	s_setprio 1
	v_mfma_f32_16x16x32_bf16 v[116:119], v[168:171], v[184:187], 0
	v_mfma_f32_16x16x32_bf16 v[116:119], v[172:175], v[188:191], v[116:119]
	v_mfma_f32_16x16x32_bf16 v[108:111], v[176:179], v[184:187], 0
	v_mfma_f32_16x16x32_bf16 v[108:111], v[180:183], v[188:191], v[108:111]
	v_mfma_f32_16x16x32_bf16 v[100:103], v[168:171], v[192:195], 0
	v_mfma_f32_16x16x32_bf16 v[100:103], v[172:175], v[204:207], v[100:103]
	v_mfma_f32_16x16x32_bf16 v[92:95], v[176:179], v[192:195], 0
	v_mfma_f32_16x16x32_bf16 v[92:95], v[180:183], v[204:207], v[92:95]
	v_mfma_f32_16x16x32_bf16 v[84:87], v[168:171], v[208:211], 0
	v_mfma_f32_16x16x32_bf16 v[84:87], v[172:175], v[212:215], v[84:87]
	v_mfma_f32_16x16x32_bf16 v[76:79], v[176:179], v[208:211], 0
	v_mfma_f32_16x16x32_bf16 v[76:79], v[180:183], v[212:215], v[76:79]
	v_mfma_f32_16x16x32_bf16 v[72:75], v[168:171], v[216:219], 0
	v_mfma_f32_16x16x32_bf16 v[72:75], v[172:175], v[220:223], v[72:75]
	s_setprio 2
	s_barrier
	v_mfma_f32_16x16x32_bf16 v[68:71], v[176:179], v[216:219], 0
	v_mfma_f32_16x16x32_bf16 v[68:71], v[180:183], v[220:223], v[68:71]
	s_setprio 0
	s_add_i32 s30, s31, s53
	v_lshl_add_u64 v[156:157], s[40:41], 0, v[2:3]
	s_mov_b32 m0, s30
	ds_read_b128 v[184:187], v147 offset:16384
	ds_read_b128 v[188:191], v147 offset:17408
	ds_read_b128 v[192:195], v147 offset:18432
	ds_read_b128 v[204:207], v147 offset:19456
	ds_read_b128 v[208:211], v147 offset:20480
	ds_read_b128 v[212:215], v147 offset:21504
	ds_read_b128 v[216:219], v147 offset:22528
	ds_read_b128 v[220:223], v147 offset:23552
	global_load_lds_dwordx4 v[156:157], off
	s_add_i32 m0, s30, 0x2000
	s_add_u32 s30, s40, 0x80000
	v_lshl_add_u64 v[196:197], s[40:41], 0, v[0:1]
	s_addc_u32 s31, s41, 0
	s_add_i32 s27, s27, s53
	global_load_lds_dwordx4 v[196:197], off
	v_lshl_add_u64 v[224:225], s[30:31], 0, v[2:3]
	s_mov_b32 m0, s27
	v_lshl_add_u64 v[226:227], s[42:43], 0, v[132:133]
	global_load_lds_dwordx4 v[224:225], off
	v_lshl_add_u64 v[224:225], s[30:31], 0, v[0:1]
	s_add_i32 m0, s27, 0x2000
	s_nop 0
	global_load_lds_dwordx4 v[224:225], off
	v_lshl_add_u64 v[224:225], s[42:43], 0, v[134:135]
	s_mov_b32 m0, s58
	s_nop 0
	global_load_lds_dwordx4 v[224:225], off
	s_mov_b32 m0, s59
	s_nop 0
	global_load_lds_dwordx4 v[226:227], off
	s_waitcnt vmcnt(8)
	s_waitcnt lgkmcnt(0)
	s_barrier
; #define PG8_STAGE(bufoff, gbase, voff) do { _Pragma("unroll") for (int _i = 0; _i < 2; ++_i) \
;         __builtin_amdgcn_global_load_lds((const unsigned*)((const char*)(gbase) + (voff)[_i]), (LAS unsigned*)(lds + (bufoff) + ldsw + _i * 8192), 16, 0, 0); } while (0)
; #define PG8_LDA(dst, b, h) do { _Pragma("unroll") for (int m = 0; m < 4; ++m) _Pragma("unroll") for (int k = 0; k < 2; ++k) dst[m][k] = *(const LAS bf16x8*)(lds + PG8_SA(b, h) + aoff + m * 2048 + k * 1024); } while (0)
; #define PG8_LDB(dst, b, h) do { _Pragma("unroll") for (int n = 0; n < 2; ++n) _Pragma("unroll") for (int k = 0; k < 2; ++k) dst[n][k] = *(const LAS bf16x8*)(lds + PG8_SB(b, h) + boff + n * 2048 + k * 1024); } while (0)
; #define PG8_MMA(ai, bj, At, Bt) do { __builtin_amdgcn_s_setprio(1); _Pragma("unroll") for (int m = 0; m < 4; ++m) _Pragma("unroll") for (int n = 0; n < 2; ++n) _Pragma("unroll") for (int k = 0; k < 2; ++k) \
;         acc[ai][bj][m][n] = __builtin_amdgcn_mfma_f32_16x16x32_bf16(Bt[n][k], At[m][k], acc[ai][bj][m][n], 0, 0, 0); __builtin_amdgcn_s_setprio(0); } while (0)
; #define PG8_WAIT_V(n) asm volatile("s_waitcnt vmcnt(" #n ")" ::: "memory")
; #define PG8_WAIT_L(n) asm volatile("s_waitcnt lgkmcnt(" #n ")" ::: "memory")
; #define PG8_BAR __builtin_amdgcn_s_barrier()
; #define PG8_SCHED __builtin_amdgcn_sched_barrier(0)
; template <class Epi, class Sched, bool ALIGN_EPI = true>
; __device__ __forceinline__ void gemm_phase(LAS unsigned char* lds, const Gemm g, const Sched& S, const Epi& E) {
;     ...
;             PG8_WAIT_V(8); PG8_WAIT_L(0); PG8_BAR; PG8_MMA(1, 0, At, B0); PG8_MMA(1, 1, At, B1); PG8_BAR; PG8_SCHED;
;             PG8_LDB(B0, 1, 0); PG8_LDB(B1, 1, 1); PG8_SCHED; PG8_LDA(At, 1, 0); PG8_STAGE(PG8_SA(0, 1), a2 + hA, voffA);
;             PG8_WAIT_V(8); PG8_WAIT_L(0); PG8_BAR; PG8_MMA(0, 0, At, B0); PG8_MMA(0, 1, At, B1); PG8_BAR; PG8_SCHED;
;             PG8_LDA(At, 1, 1); PG8_STAGE(PG8_SB(1, 0), b3, voffB); PG8_STAGE(PG8_SB(1, 1), b3 + hB, voffB); PG8_STAGE(PG8_SA(1, 0), a3, voffA);
;             PG8_WAIT_V(8); PG8_WAIT_L(0); PG8_BAR; PG8_MMA(1, 0, At, B0); PG8_MMA(1, 1, At, B1); PG8_BAR; PG8_SCHED;
	s_setprio 1
	s_waitcnt lgkmcnt(0)
	v_mfma_f32_16x16x32_bf16 v[64:67], v[140:143], v[184:187], 0
	v_mfma_f32_16x16x32_bf16 v[64:67], v[148:151], v[188:191], v[64:67]
	v_mfma_f32_16x16x32_bf16 v[60:63], v[152:155], v[184:187], 0
	v_mfma_f32_16x16x32_bf16 v[60:63], v[164:167], v[188:191], v[60:63]
	v_mfma_f32_16x16x32_bf16 v[56:59], v[140:143], v[192:195], 0
	v_mfma_f32_16x16x32_bf16 v[56:59], v[148:151], v[204:207], v[56:59]
	v_mfma_f32_16x16x32_bf16 v[48:51], v[152:155], v[192:195], 0
	v_mfma_f32_16x16x32_bf16 v[48:51], v[164:167], v[204:207], v[48:51]
	v_mfma_f32_16x16x32_bf16 v[40:43], v[140:143], v[208:211], 0
	v_mfma_f32_16x16x32_bf16 v[40:43], v[148:151], v[212:215], v[40:43]
	v_mfma_f32_16x16x32_bf16 v[32:35], v[152:155], v[208:211], 0
	v_mfma_f32_16x16x32_bf16 v[32:35], v[164:167], v[212:215], v[32:35]
	v_mfma_f32_16x16x32_bf16 v[24:27], v[140:143], v[216:219], 0
	v_mfma_f32_16x16x32_bf16 v[24:27], v[148:151], v[220:223], v[24:27]
	v_mfma_f32_16x16x32_bf16 v[16:19], v[152:155], v[216:219], 0
	v_mfma_f32_16x16x32_bf16 v[16:19], v[164:167], v[220:223], v[16:19]
	s_setprio 0
	s_setprio 1
	v_mfma_f32_16x16x32_bf16 v[52:55], v[168:171], v[184:187], 0
	v_mfma_f32_16x16x32_bf16 v[52:55], v[172:175], v[188:191], v[52:55]
	v_mfma_f32_16x16x32_bf16 v[44:47], v[176:179], v[184:187], 0
	v_mfma_f32_16x16x32_bf16 v[44:47], v[180:183], v[188:191], v[44:47]
	v_mfma_f32_16x16x32_bf16 v[36:39], v[168:171], v[192:195], 0
	v_mfma_f32_16x16x32_bf16 v[36:39], v[172:175], v[204:207], v[36:39]
	v_mfma_f32_16x16x32_bf16 v[28:31], v[176:179], v[192:195], 0
	v_mfma_f32_16x16x32_bf16 v[28:31], v[180:183], v[204:207], v[28:31]
	v_mfma_f32_16x16x32_bf16 v[20:23], v[168:171], v[208:211], 0
	v_mfma_f32_16x16x32_bf16 v[20:23], v[172:175], v[212:215], v[20:23]
	v_mfma_f32_16x16x32_bf16 v[12:15], v[176:179], v[208:211], 0
	v_mfma_f32_16x16x32_bf16 v[12:15], v[180:183], v[212:215], v[12:15]
	v_mfma_f32_16x16x32_bf16 v[8:11], v[168:171], v[216:219], 0
	v_mfma_f32_16x16x32_bf16 v[8:11], v[172:175], v[220:223], v[8:11]
	s_setprio 2
	s_barrier
	v_mfma_f32_16x16x32_bf16 v[4:7], v[176:179], v[216:219], 0
	v_mfma_f32_16x16x32_bf16 v[4:7], v[180:183], v[220:223], v[4:7]
	s_setprio 0
	s_add_i32 s27, 0, 0x18000
	v_add_u32_e32 v158, s27, v145
	s_add_i32 s65, 0, 0x1c000
	ds_read_b128 v[140:143], v158
	ds_read_b128 v[148:151], v158 offset:1024
	ds_read_b128 v[152:155], v158 offset:2048
	ds_read_b128 v[164:167], v158 offset:3072
	v_add_u32_e32 v158, s65, v145
	ds_read_b128 v[168:171], v158
	ds_read_b128 v[172:175], v158 offset:1024
	ds_read_b128 v[176:179], v158 offset:2048
	ds_read_b128 v[180:183], v158 offset:3072
	s_add_u32 s30, s42, 0x80000
	s_addc_u32 s31, s43, 0
	s_mov_b32 m0, s60
	v_lshl_add_u64 v[228:229], s[30:31], 0, v[134:135]
	ds_read_b128 v[184:187], v147 offset:32768
	ds_read_b128 v[188:191], v147 offset:33792
	ds_read_b128 v[192:195], v147 offset:34816
	ds_read_b128 v[204:207], v147 offset:35840
	ds_read_b128 v[208:211], v147 offset:36864
	ds_read_b128 v[212:215], v147 offset:37888
	ds_read_b128 v[216:219], v147 offset:38912
	ds_read_b128 v[220:223], v147 offset:39936
	global_load_lds_dwordx4 v[228:229], off
	v_lshl_add_u64 v[228:229], s[30:31], 0, v[132:133]
	s_mov_b32 m0, s61
	s_nop 0
	global_load_lds_dwordx4 v[228:229], off
	s_waitcnt vmcnt(8)
	s_waitcnt lgkmcnt(0)
	s_barrier
	s_setprio 1
	s_waitcnt lgkmcnt(0)
	v_mfma_f32_16x16x32_bf16 v[128:131], v[140:143], v[184:187], v[128:131]
	v_mfma_f32_16x16x32_bf16 v[128:131], v[148:151], v[188:191], v[128:131]
	v_mfma_f32_16x16x32_bf16 v[124:127], v[152:155], v[184:187], v[124:127]
	v_mfma_f32_16x16x32_bf16 v[124:127], v[164:167], v[188:191], v[124:127]
	v_mfma_f32_16x16x32_bf16 v[120:123], v[140:143], v[192:195], v[120:123]
	v_mfma_f32_16x16x32_bf16 v[120:123], v[148:151], v[204:207], v[120:123]
	v_mfma_f32_16x16x32_bf16 v[112:115], v[152:155], v[192:195], v[112:115]
	v_mfma_f32_16x16x32_bf16 v[112:115], v[164:167], v[204:207], v[112:115]
	v_mfma_f32_16x16x32_bf16 v[104:107], v[140:143], v[208:211], v[104:107]
	v_mfma_f32_16x16x32_bf16 v[104:107], v[148:151], v[212:215], v[104:107]
	v_mfma_f32_16x16x32_bf16 v[96:99], v[152:155], v[208:211], v[96:99]
	v_mfma_f32_16x16x32_bf16 v[96:99], v[164:167], v[212:215], v[96:99]
	v_mfma_f32_16x16x32_bf16 v[88:91], v[140:143], v[216:219], v[88:91]
	v_mfma_f32_16x16x32_bf16 v[88:91], v[148:151], v[220:223], v[88:91]
	v_mfma_f32_16x16x32_bf16 v[80:83], v[152:155], v[216:219], v[80:83]
	v_mfma_f32_16x16x32_bf16 v[80:83], v[164:167], v[220:223], v[80:83]
	s_setprio 0
	s_setprio 1
	v_mfma_f32_16x16x32_bf16 v[116:119], v[168:171], v[184:187], v[116:119]
	v_mfma_f32_16x16x32_bf16 v[116:119], v[172:175], v[188:191], v[116:119]
	v_mfma_f32_16x16x32_bf16 v[108:111], v[176:179], v[184:187], v[108:111]
	v_mfma_f32_16x16x32_bf16 v[108:111], v[180:183], v[188:191], v[108:111]
	v_mfma_f32_16x16x32_bf16 v[100:103], v[168:171], v[192:195], v[100:103]
	v_mfma_f32_16x16x32_bf16 v[100:103], v[172:175], v[204:207], v[100:103]
	v_mfma_f32_16x16x32_bf16 v[92:95], v[176:179], v[192:195], v[92:95]
	v_mfma_f32_16x16x32_bf16 v[92:95], v[180:183], v[204:207], v[92:95]
	v_mfma_f32_16x16x32_bf16 v[84:87], v[168:171], v[208:211], v[84:87]
	v_mfma_f32_16x16x32_bf16 v[84:87], v[172:175], v[212:215], v[84:87]
	v_mfma_f32_16x16x32_bf16 v[76:79], v[176:179], v[208:211], v[76:79]
	v_mfma_f32_16x16x32_bf16 v[76:79], v[180:183], v[212:215], v[76:79]
	v_mfma_f32_16x16x32_bf16 v[72:75], v[168:171], v[216:219], v[72:75]
	v_mfma_f32_16x16x32_bf16 v[72:75], v[172:175], v[220:223], v[72:75]
	s_setprio 2
	s_barrier
; #define PG8_STAGE(bufoff, gbase, voff) do { _Pragma("unroll") for (int _i = 0; _i < 2; ++_i) \
;         __builtin_amdgcn_global_load_lds((const unsigned*)((const char*)(gbase) + (voff)[_i]), (LAS unsigned*)(lds + (bufoff) + ldsw + _i * 8192), 16, 0, 0); } while (0)
; #define PG8_LDA(dst, b, h) do { _Pragma("unroll") for (int m = 0; m < 4; ++m) _Pragma("unroll") for (int k = 0; k < 2; ++k) dst[m][k] = *(const LAS bf16x8*)(lds + PG8_SA(b, h) + aoff + m * 2048 + k * 1024); } while (0)
; #define PG8_LDB(dst, b, h) do { _Pragma("unroll") for (int n = 0; n < 2; ++n) _Pragma("unroll") for (int k = 0; k < 2; ++k) dst[n][k] = *(const LAS bf16x8*)(lds + PG8_SB(b, h) + boff + n * 2048 + k * 1024); } while (0)
; #define PG8_WAIT_V(n) asm volatile("s_waitcnt vmcnt(" #n ")" ::: "memory")
; #define PG8_BAR __builtin_amdgcn_s_barrier()
; template <class Epi, class Sched, bool ALIGN_EPI = true>
; __device__ __forceinline__ void gemm_phase(LAS unsigned char* lds, const Gemm g, const Sched& S, const Epi& E) {
;     ...
;         for (int t = 0; t < nt; t += 2) {
;             const bool last = (t == nt - 2);
;             const char* a1 = cA + (size_t)(t + 1) * kstep;
;             const char* a2 = last ? nA : cA + (size_t)(t + 2) * kstep; const char* b2 = last ? nB : cB + (size_t)(t + 2) * kstep;
;             const char* a3 = a2 + kstep; const char* b3 = b2 + kstep;
;             PG8_LDB(B0, 0, 0); PG8_LDB(B1, 0, 1); PG8_SCHED; PG8_LDA(At, 0, 0); PG8_STAGE(PG8_SA(1, 1), a1 + hA, voffA);
;             PG8_WAIT_V(8); PG8_WAIT_L(0); PG8_BAR; PG8_MMA(0, 0, At, B0); PG8_MMA(0, 1, At, B1); PG8_BAR; PG8_SCHED;
;             PG8_LDA(At, 0, 1); PG8_STAGE(PG8_SB(0, 0), b2, voffB); PG8_STAGE(PG8_SB(0, 1), b2 + hB, voffB); PG8_STAGE(PG8_SA(0, 0), a2, voffA);
;             PG8_WAIT_V(8); PG8_WAIT_L(0); PG8_BAR; PG8_MMA(1, 0, At, B0); PG8_MMA(1, 1, At, B1); PG8_BAR; PG8_SCHED;
;             PG8_LDB(B0, 1, 0); PG8_LDB(B1, 1, 1); PG8_SCHED; PG8_LDA(At, 1, 0); PG8_STAGE(PG8_SA(0, 1), a2 + hA, voffA);
;             PG8_WAIT_V(8); PG8_WAIT_L(0); PG8_BAR; PG8_MMA(0, 0, At, B0); PG8_MMA(0, 1, At, B1); PG8_BAR; PG8_SCHED;
;             PG8_LDA(At, 1, 1); PG8_STAGE(PG8_SB(1, 0), b3, voffB); PG8_STAGE(PG8_SB(1, 1), b3 + hB, voffB); PG8_STAGE(PG8_SA(1, 0), a3, voffA);
;             PG8_WAIT_V(8); PG8_WAIT_L(0); PG8_BAR; PG8_MMA(1, 0, At, B0); PG8_MMA(1, 1, At, B1); PG8_BAR; PG8_SCHED;
	v_mfma_f32_16x16x32_bf16 v[68:71], v[176:179], v[216:219], v[68:71]
	v_mfma_f32_16x16x32_bf16 v[68:71], v[180:183], v[220:223], v[68:71]
	s_setprio 0
	s_add_i32 s27, s27, s53
	v_lshl_add_u64 v[156:157], v[156:157], 0, s[86:87]
	s_mov_b32 m0, s27
	ds_read_b128 v[184:187], v147 offset:49152
	ds_read_b128 v[188:191], v147 offset:50176
	ds_read_b128 v[192:195], v147 offset:51200
	ds_read_b128 v[204:207], v147 offset:52224
	ds_read_b128 v[208:211], v147 offset:53248
	ds_read_b128 v[212:215], v147 offset:54272
	ds_read_b128 v[216:219], v147 offset:55296
	ds_read_b128 v[220:223], v147 offset:56320
	global_load_lds_dwordx4 v[156:157], off
	s_add_i32 m0, s27, 0x2000
	s_add_u32 s30, s40, 0x80080
	v_lshl_add_u64 v[156:157], v[196:197], 0, s[86:87]
	s_addc_u32 s31, s41, 0
	s_add_i32 s27, s65, s53
	global_load_lds_dwordx4 v[156:157], off
	v_lshl_add_u64 v[156:157], s[30:31], 0, v[2:3]
	s_mov_b32 m0, s27
	s_nop 0
	global_load_lds_dwordx4 v[156:157], off
	v_lshl_add_u64 v[156:157], s[30:31], 0, v[0:1]
	s_add_i32 m0, s27, 0x2000
	s_nop 0
	global_load_lds_dwordx4 v[156:157], off
	v_lshl_add_u64 v[156:157], v[224:225], 0, s[86:87]
	s_mov_b32 m0, s62
	s_nop 0
	global_load_lds_dwordx4 v[156:157], off
	v_lshl_add_u64 v[156:157], v[226:227], 0, s[86:87]
	s_mov_b32 m0, s63
	s_nop 0
	global_load_lds_dwordx4 v[156:157], off
	s_add_i32 s26, s26, 2
	s_add_u32 s38, s38, 0x100
	s_addc_u32 s39, s39, 0
	s_add_u32 s24, s24, 0x100
	s_addc_u32 s25, s25, 0
	s_add_u32 s27, s38, 0xfff80080
	s_addc_u32 s30, s39, -1
	s_add_i32 s31, 0, 0x10000
	s_cmp_eq_u32 s26, 28
	s_cselect_b32 s43, s11, s30
	s_cselect_b32 s42, s18, s27
	s_cselect_b32 s41, s9, s25
	s_cselect_b32 s40, s19, s24
	s_add_i32 s27, 0, 0x14000
	s_waitcnt vmcnt(8)
	s_waitcnt lgkmcnt(0)
	s_barrier
	s_setprio 1
	s_waitcnt lgkmcnt(0)
	v_mfma_f32_16x16x32_bf16 v[64:67], v[140:143], v[184:187], v[64:67]
	v_mfma_f32_16x16x32_bf16 v[64:67], v[148:151], v[188:191], v[64:67]
	v_mfma_f32_16x16x32_bf16 v[60:63], v[152:155], v[184:187], v[60:63]
	v_mfma_f32_16x16x32_bf16 v[60:63], v[164:167], v[188:191], v[60:63]
	v_mfma_f32_16x16x32_bf16 v[56:59], v[140:143], v[192:195], v[56:59]
	v_mfma_f32_16x16x32_bf16 v[56:59], v[148:151], v[204:207], v[56:59]
	v_mfma_f32_16x16x32_bf16 v[48:51], v[152:155], v[192:195], v[48:51]
	v_mfma_f32_16x16x32_bf16 v[48:51], v[164:167], v[204:207], v[48:51]
	v_mfma_f32_16x16x32_bf16 v[40:43], v[140:143], v[208:211], v[40:43]
	v_mfma_f32_16x16x32_bf16 v[40:43], v[148:151], v[212:215], v[40:43]
	v_mfma_f32_16x16x32_bf16 v[32:35], v[152:155], v[208:211], v[32:35]
	v_mfma_f32_16x16x32_bf16 v[32:35], v[164:167], v[212:215], v[32:35]
	v_mfma_f32_16x16x32_bf16 v[24:27], v[140:143], v[216:219], v[24:27]
	v_mfma_f32_16x16x32_bf16 v[24:27], v[148:151], v[220:223], v[24:27]
	v_mfma_f32_16x16x32_bf16 v[16:19], v[152:155], v[216:219], v[16:19]
	v_mfma_f32_16x16x32_bf16 v[16:19], v[164:167], v[220:223], v[16:19]
	s_setprio 0
	s_setprio 1
	v_mfma_f32_16x16x32_bf16 v[52:55], v[168:171], v[184:187], v[52:55]
	v_mfma_f32_16x16x32_bf16 v[52:55], v[172:175], v[188:191], v[52:55]
	v_mfma_f32_16x16x32_bf16 v[44:47], v[176:179], v[184:187], v[44:47]
	v_mfma_f32_16x16x32_bf16 v[44:47], v[180:183], v[188:191], v[44:47]
	v_mfma_f32_16x16x32_bf16 v[36:39], v[168:171], v[192:195], v[36:39]
	v_mfma_f32_16x16x32_bf16 v[36:39], v[172:175], v[204:207], v[36:39]
	v_mfma_f32_16x16x32_bf16 v[28:31], v[176:179], v[192:195], v[28:31]
	v_mfma_f32_16x16x32_bf16 v[28:31], v[180:183], v[204:207], v[28:31]
	v_mfma_f32_16x16x32_bf16 v[20:23], v[168:171], v[208:211], v[20:23]
	v_mfma_f32_16x16x32_bf16 v[20:23], v[172:175], v[212:215], v[20:23]
	v_mfma_f32_16x16x32_bf16 v[12:15], v[176:179], v[208:211], v[12:15]
	v_mfma_f32_16x16x32_bf16 v[12:15], v[180:183], v[212:215], v[12:15]
	v_mfma_f32_16x16x32_bf16 v[8:11], v[168:171], v[216:219], v[8:11]
	v_mfma_f32_16x16x32_bf16 v[8:11], v[172:175], v[220:223], v[8:11]
	s_setprio 2
	s_barrier
	v_mfma_f32_16x16x32_bf16 v[4:7], v[176:179], v[216:219], v[4:7]
	v_mfma_f32_16x16x32_bf16 v[4:7], v[180:183], v[220:223], v[4:7]
	s_setprio 0
	s_cmp_gt_u32 s26, 29
	s_cbranch_scc1 .Lpeel_exit_218
.LBB0_218:
	v_add_u32_e32 v156, s31, v145
	ds_read_b128 v[140:143], v156
	ds_read_b128 v[148:151], v156 offset:1024
	ds_read_b128 v[152:155], v156 offset:2048
	ds_read_b128 v[164:167], v156 offset:3072
	v_add_u32_e32 v156, s27, v145
	ds_read_b128 v[168:171], v156
	ds_read_b128 v[172:175], v156 offset:1024
	ds_read_b128 v[176:179], v156 offset:2048
	ds_read_b128 v[180:183], v156 offset:3072
	v_lshl_add_u64 v[156:157], s[38:39], 0, v[136:137]
	s_add_i32 m0, s58, 0xc000
	ds_read_b128 v[184:187], v147
	ds_read_b128 v[188:191], v147 offset:1024
	ds_read_b128 v[192:195], v147 offset:2048
	ds_read_b128 v[204:207], v147 offset:3072
	ds_read_b128 v[208:211], v147 offset:4096
	ds_read_b128 v[212:215], v147 offset:5120
	ds_read_b128 v[216:219], v147 offset:6144
	ds_read_b128 v[220:223], v147 offset:7168
	global_load_lds_dwordx4 v[156:157], off
	v_lshl_add_u64 v[156:157], s[38:39], 0, v[138:139]
	s_add_i32 m0, s58, 0xe000
	s_nop 0
	global_load_lds_dwordx4 v[156:157], off
	s_waitcnt vmcnt(8)
	s_waitcnt lgkmcnt(0)
	s_barrier
; #define PG8_STAGE(bufoff, gbase, voff) do { _Pragma("unroll") for (int _i = 0; _i < 2; ++_i) \
;         __builtin_amdgcn_global_load_lds((const unsigned*)((const char*)(gbase) + (voff)[_i]), (LAS unsigned*)(lds + (bufoff) + ldsw + _i * 8192), 16, 0, 0); } while (0)
; #define PG8_LDA(dst, b, h) do { _Pragma("unroll") for (int m = 0; m < 4; ++m) _Pragma("unroll") for (int k = 0; k < 2; ++k) dst[m][k] = *(const LAS bf16x8*)(lds + PG8_SA(b, h) + aoff + m * 2048 + k * 1024); } while (0)
; #define PG8_LDB(dst, b, h) do { _Pragma("unroll") for (int n = 0; n < 2; ++n) _Pragma("unroll") for (int k = 0; k < 2; ++k) dst[n][k] = *(const LAS bf16x8*)(lds + PG8_SB(b, h) + boff + n * 2048 + k * 1024); } while (0)
; #define PG8_MMA(ai, bj, At, Bt) do { __builtin_amdgcn_s_setprio(1); _Pragma("unroll") for (int m = 0; m < 4; ++m) _Pragma("unroll") for (int n = 0; n < 2; ++n) _Pragma("unroll") for (int k = 0; k < 2; ++k) \
;         acc[ai][bj][m][n] = __builtin_amdgcn_mfma_f32_16x16x32_bf16(Bt[n][k], At[m][k], acc[ai][bj][m][n], 0, 0, 0); __builtin_amdgcn_s_setprio(0); } while (0)
; #define PG8_WAIT_V(n) asm volatile("s_waitcnt vmcnt(" #n ")" ::: "memory")
; #define PG8_BAR __builtin_amdgcn_s_barrier()
; template <class Epi, class Sched, bool ALIGN_EPI = true>
; __device__ __forceinline__ void gemm_phase(LAS unsigned char* lds, const Gemm g, const Sched& S, const Epi& E) {
;     ...
;             PG8_LDB(B0, 0, 0); PG8_LDB(B1, 0, 1); PG8_SCHED; PG8_LDA(At, 0, 0); PG8_STAGE(PG8_SA(1, 1), a1 + hA, voffA);
;             PG8_WAIT_V(8); PG8_WAIT_L(0); PG8_BAR; PG8_MMA(0, 0, At, B0); PG8_MMA(0, 1, At, B1); PG8_BAR; PG8_SCHED;
;             PG8_LDA(At, 0, 1); PG8_STAGE(PG8_SB(0, 0), b2, voffB); PG8_STAGE(PG8_SB(0, 1), b2 + hB, voffB); PG8_STAGE(PG8_SA(0, 0), a2, voffA);
;             PG8_WAIT_V(8); PG8_WAIT_L(0); PG8_BAR; PG8_MMA(1, 0, At, B0); PG8_MMA(1, 1, At, B1); PG8_BAR; PG8_SCHED;
;             PG8_LDB(B0, 1, 0); PG8_LDB(B1, 1, 1); PG8_SCHED; PG8_LDA(At, 1, 0); PG8_STAGE(PG8_SA(0, 1), a2 + hA, voffA);
;             PG8_WAIT_V(8); PG8_WAIT_L(0); PG8_BAR; PG8_MMA(0, 0, At, B0); PG8_MMA(0, 1, At, B1); PG8_BAR; PG8_SCHED;
;             PG8_LDA(At, 1, 1); PG8_STAGE(PG8_SB(1, 0), b3, voffB); PG8_STAGE(PG8_SB(1, 1), b3 + hB, voffB); PG8_STAGE(PG8_SA(1, 0), a3, voffA);
;             PG8_WAIT_V(8); PG8_WAIT_L(0); PG8_BAR; PG8_MMA(1, 0, At, B0); PG8_MMA(1, 1, At, B1); PG8_BAR; PG8_SCHED;
	s_setprio 1
	s_waitcnt lgkmcnt(0)
	v_mfma_f32_16x16x32_bf16 v[128:131], v[140:143], v[184:187], v[128:131]
	v_mfma_f32_16x16x32_bf16 v[128:131], v[148:151], v[188:191], v[128:131]
	v_mfma_f32_16x16x32_bf16 v[124:127], v[152:155], v[184:187], v[124:127]
	v_mfma_f32_16x16x32_bf16 v[124:127], v[164:167], v[188:191], v[124:127]
	v_mfma_f32_16x16x32_bf16 v[120:123], v[140:143], v[192:195], v[120:123]
	v_mfma_f32_16x16x32_bf16 v[120:123], v[148:151], v[204:207], v[120:123]
	v_mfma_f32_16x16x32_bf16 v[112:115], v[152:155], v[192:195], v[112:115]
	v_mfma_f32_16x16x32_bf16 v[112:115], v[164:167], v[204:207], v[112:115]
	v_mfma_f32_16x16x32_bf16 v[104:107], v[140:143], v[208:211], v[104:107]
	v_mfma_f32_16x16x32_bf16 v[104:107], v[148:151], v[212:215], v[104:107]
	v_mfma_f32_16x16x32_bf16 v[96:99], v[152:155], v[208:211], v[96:99]
	v_mfma_f32_16x16x32_bf16 v[96:99], v[164:167], v[212:215], v[96:99]
	v_mfma_f32_16x16x32_bf16 v[88:91], v[140:143], v[216:219], v[88:91]
	v_mfma_f32_16x16x32_bf16 v[88:91], v[148:151], v[220:223], v[88:91]
	v_mfma_f32_16x16x32_bf16 v[80:83], v[152:155], v[216:219], v[80:83]
	v_mfma_f32_16x16x32_bf16 v[80:83], v[164:167], v[220:223], v[80:83]
	s_setprio 0
	s_setprio 1
	v_mfma_f32_16x16x32_bf16 v[116:119], v[168:171], v[184:187], v[116:119]
	v_mfma_f32_16x16x32_bf16 v[116:119], v[172:175], v[188:191], v[116:119]
	v_mfma_f32_16x16x32_bf16 v[108:111], v[176:179], v[184:187], v[108:111]
	v_mfma_f32_16x16x32_bf16 v[108:111], v[180:183], v[188:191], v[108:111]
	v_mfma_f32_16x16x32_bf16 v[100:103], v[168:171], v[192:195], v[100:103]
	v_mfma_f32_16x16x32_bf16 v[100:103], v[172:175], v[204:207], v[100:103]
	v_mfma_f32_16x16x32_bf16 v[92:95], v[176:179], v[192:195], v[92:95]
	v_mfma_f32_16x16x32_bf16 v[92:95], v[180:183], v[204:207], v[92:95]
	v_mfma_f32_16x16x32_bf16 v[84:87], v[168:171], v[208:211], v[84:87]
	v_mfma_f32_16x16x32_bf16 v[84:87], v[172:175], v[212:215], v[84:87]
	v_mfma_f32_16x16x32_bf16 v[76:79], v[176:179], v[208:211], v[76:79]
	v_mfma_f32_16x16x32_bf16 v[76:79], v[180:183], v[212:215], v[76:79]
	v_mfma_f32_16x16x32_bf16 v[72:75], v[168:171], v[216:219], v[72:75]
	v_mfma_f32_16x16x32_bf16 v[72:75], v[172:175], v[220:223], v[72:75]
	s_setprio 2
	s_barrier
	v_mfma_f32_16x16x32_bf16 v[68:71], v[176:179], v[216:219], v[68:71]
	v_mfma_f32_16x16x32_bf16 v[68:71], v[180:183], v[220:223], v[68:71]
	s_setprio 0
	s_add_i32 s30, s31, s53
	v_lshl_add_u64 v[156:157], s[40:41], 0, v[2:3]
	s_mov_b32 m0, s30
	ds_read_b128 v[184:187], v147 offset:16384
	ds_read_b128 v[188:191], v147 offset:17408
	ds_read_b128 v[192:195], v147 offset:18432
	ds_read_b128 v[204:207], v147 offset:19456
	ds_read_b128 v[208:211], v147 offset:20480
	ds_read_b128 v[212:215], v147 offset:21504
	ds_read_b128 v[216:219], v147 offset:22528
	ds_read_b128 v[220:223], v147 offset:23552
	global_load_lds_dwordx4 v[156:157], off
	s_add_i32 m0, s30, 0x2000
	s_add_u32 s30, s40, 0x80000
	v_lshl_add_u64 v[196:197], s[40:41], 0, v[0:1]
	s_addc_u32 s31, s41, 0
	s_add_i32 s27, s27, s53
	global_load_lds_dwordx4 v[196:197], off
	v_lshl_add_u64 v[224:225], s[30:31], 0, v[2:3]
	s_mov_b32 m0, s27
	v_lshl_add_u64 v[226:227], s[42:43], 0, v[132:133]
	global_load_lds_dwordx4 v[224:225], off
	v_lshl_add_u64 v[224:225], s[30:31], 0, v[0:1]
	s_add_i32 m0, s27, 0x2000
	s_nop 0
	global_load_lds_dwordx4 v[224:225], off
	v_lshl_add_u64 v[224:225], s[42:43], 0, v[134:135]
	s_mov_b32 m0, s58
	s_nop 0
	global_load_lds_dwordx4 v[224:225], off
	s_mov_b32 m0, s59
	s_nop 0
	global_load_lds_dwordx4 v[226:227], off
	s_waitcnt vmcnt(8)
	s_waitcnt lgkmcnt(0)
	s_barrier
	s_setprio 1
	s_waitcnt lgkmcnt(0)
	v_mfma_f32_16x16x32_bf16 v[64:67], v[140:143], v[184:187], v[64:67]
	v_mfma_f32_16x16x32_bf16 v[64:67], v[148:151], v[188:191], v[64:67]
	v_mfma_f32_16x16x32_bf16 v[60:63], v[152:155], v[184:187], v[60:63]
	v_mfma_f32_16x16x32_bf16 v[60:63], v[164:167], v[188:191], v[60:63]
	v_mfma_f32_16x16x32_bf16 v[56:59], v[140:143], v[192:195], v[56:59]
	v_mfma_f32_16x16x32_bf16 v[56:59], v[148:151], v[204:207], v[56:59]
	v_mfma_f32_16x16x32_bf16 v[48:51], v[152:155], v[192:195], v[48:51]
	v_mfma_f32_16x16x32_bf16 v[48:51], v[164:167], v[204:207], v[48:51]
	v_mfma_f32_16x16x32_bf16 v[40:43], v[140:143], v[208:211], v[40:43]
	v_mfma_f32_16x16x32_bf16 v[40:43], v[148:151], v[212:215], v[40:43]
	v_mfma_f32_16x16x32_bf16 v[32:35], v[152:155], v[208:211], v[32:35]
	v_mfma_f32_16x16x32_bf16 v[32:35], v[164:167], v[212:215], v[32:35]
	v_mfma_f32_16x16x32_bf16 v[24:27], v[140:143], v[216:219], v[24:27]
	v_mfma_f32_16x16x32_bf16 v[24:27], v[148:151], v[220:223], v[24:27]
	v_mfma_f32_16x16x32_bf16 v[16:19], v[152:155], v[216:219], v[16:19]
	v_mfma_f32_16x16x32_bf16 v[16:19], v[164:167], v[220:223], v[16:19]
	s_setprio 0
	s_setprio 1
	v_mfma_f32_16x16x32_bf16 v[52:55], v[168:171], v[184:187], v[52:55]
	v_mfma_f32_16x16x32_bf16 v[52:55], v[172:175], v[188:191], v[52:55]
	v_mfma_f32_16x16x32_bf16 v[44:47], v[176:179], v[184:187], v[44:47]
	v_mfma_f32_16x16x32_bf16 v[44:47], v[180:183], v[188:191], v[44:47]
	v_mfma_f32_16x16x32_bf16 v[36:39], v[168:171], v[192:195], v[36:39]
	v_mfma_f32_16x16x32_bf16 v[36:39], v[172:175], v[204:207], v[36:39]
	v_mfma_f32_16x16x32_bf16 v[28:31], v[176:179], v[192:195], v[28:31]
	v_mfma_f32_16x16x32_bf16 v[28:31], v[180:183], v[204:207], v[28:31]
	v_mfma_f32_16x16x32_bf16 v[20:23], v[168:171], v[208:211], v[20:23]
	v_mfma_f32_16x16x32_bf16 v[20:23], v[172:175], v[212:215], v[20:23]
	v_mfma_f32_16x16x32_bf16 v[12:15], v[176:179], v[208:211], v[12:15]
	v_mfma_f32_16x16x32_bf16 v[12:15], v[180:183], v[212:215], v[12:15]
	v_mfma_f32_16x16x32_bf16 v[8:11], v[168:171], v[216:219], v[8:11]
	v_mfma_f32_16x16x32_bf16 v[8:11], v[172:175], v[220:223], v[8:11]
	s_setprio 2
	s_barrier
; #define PG8_STAGE(bufoff, gbase, voff) do { _Pragma("unroll") for (int _i = 0; _i < 2; ++_i) \
;         __builtin_amdgcn_global_load_lds((const unsigned*)((const char*)(gbase) + (voff)[_i]), (LAS unsigned*)(lds + (bufoff) + ldsw + _i * 8192), 16, 0, 0); } while (0)
; #define PG8_LDA(dst, b, h) do { _Pragma("unroll") for (int m = 0; m < 4; ++m) _Pragma("unroll") for (int k = 0; k < 2; ++k) dst[m][k] = *(const LAS bf16x8*)(lds + PG8_SA(b, h) + aoff + m * 2048 + k * 1024); } while (0)
; #define PG8_LDB(dst, b, h) do { _Pragma("unroll") for (int n = 0; n < 2; ++n) _Pragma("unroll") for (int k = 0; k < 2; ++k) dst[n][k] = *(const LAS bf16x8*)(lds + PG8_SB(b, h) + boff + n * 2048 + k * 1024); } while (0)
; #define PG8_MMA(ai, bj, At, Bt) do { __builtin_amdgcn_s_setprio(1); _Pragma("unroll") for (int m = 0; m < 4; ++m) _Pragma("unroll") for (int n = 0; n < 2; ++n) _Pragma("unroll") for (int k = 0; k < 2; ++k) \
;         acc[ai][bj][m][n] = __builtin_amdgcn_mfma_f32_16x16x32_bf16(Bt[n][k], At[m][k], acc[ai][bj][m][n], 0, 0, 0); __builtin_amdgcn_s_setprio(0); } while (0)
; #define PG8_WAIT_V(n) asm volatile("s_waitcnt vmcnt(" #n ")" ::: "memory")
; #define PG8_WAIT_L(n) asm volatile("s_waitcnt lgkmcnt(" #n ")" ::: "memory")
; #define PG8_BAR __builtin_amdgcn_s_barrier()
; #define PG8_SCHED __builtin_amdgcn_sched_barrier(0)
; template <class Epi, class Sched, bool ALIGN_EPI = true>
; __device__ __forceinline__ void gemm_phase(LAS unsigned char* lds, const Gemm g, const Sched& S, const Epi& E) {
;     ...
;             PG8_LDB(B0, 1, 0); PG8_LDB(B1, 1, 1); PG8_SCHED; PG8_LDA(At, 1, 0); PG8_STAGE(PG8_SA(0, 1), a2 + hA, voffA);
;             PG8_WAIT_V(8); PG8_WAIT_L(0); PG8_BAR; PG8_MMA(0, 0, At, B0); PG8_MMA(0, 1, At, B1); PG8_BAR; PG8_SCHED;
	v_mfma_f32_16x16x32_bf16 v[4:7], v[176:179], v[216:219], v[4:7]
	v_mfma_f32_16x16x32_bf16 v[4:7], v[180:183], v[220:223], v[4:7]
	s_setprio 0
	s_add_i32 s27, 0, 0x18000
	v_add_u32_e32 v158, s27, v145
	s_add_i32 s65, 0, 0x1c000
	ds_read_b128 v[140:143], v158
	ds_read_b128 v[148:151], v158 offset:1024
	ds_read_b128 v[152:155], v158 offset:2048
	ds_read_b128 v[164:167], v158 offset:3072
	v_add_u32_e32 v158, s65, v145
	ds_read_b128 v[168:171], v158
	ds_read_b128 v[172:175], v158 offset:1024
	ds_read_b128 v[176:179], v158 offset:2048
	ds_read_b128 v[180:183], v158 offset:3072
	s_add_u32 s30, s42, 0x80000
	s_addc_u32 s31, s43, 0
	s_mov_b32 m0, s60
	v_lshl_add_u64 v[228:229], s[30:31], 0, v[134:135]
	ds_read_b128 v[184:187], v147 offset:32768
	ds_read_b128 v[188:191], v147 offset:33792
	ds_read_b128 v[192:195], v147 offset:34816
	ds_read_b128 v[204:207], v147 offset:35840
	ds_read_b128 v[208:211], v147 offset:36864
	ds_read_b128 v[212:215], v147 offset:37888
	ds_read_b128 v[216:219], v147 offset:38912
	ds_read_b128 v[220:223], v147 offset:39936
	global_load_lds_dwordx4 v[228:229], off
	v_lshl_add_u64 v[228:229], s[30:31], 0, v[132:133]
	s_mov_b32 m0, s61
	s_nop 0
	global_load_lds_dwordx4 v[228:229], off
	s_waitcnt vmcnt(8)
	s_waitcnt lgkmcnt(0)
	s_barrier
	s_setprio 1
	s_waitcnt lgkmcnt(0)
	v_mfma_f32_16x16x32_bf16 v[128:131], v[140:143], v[184:187], v[128:131]
	v_mfma_f32_16x16x32_bf16 v[128:131], v[148:151], v[188:191], v[128:131]
	v_mfma_f32_16x16x32_bf16 v[124:127], v[152:155], v[184:187], v[124:127]
	v_mfma_f32_16x16x32_bf16 v[124:127], v[164:167], v[188:191], v[124:127]
	v_mfma_f32_16x16x32_bf16 v[120:123], v[140:143], v[192:195], v[120:123]
	v_mfma_f32_16x16x32_bf16 v[120:123], v[148:151], v[204:207], v[120:123]
	v_mfma_f32_16x16x32_bf16 v[112:115], v[152:155], v[192:195], v[112:115]
	v_mfma_f32_16x16x32_bf16 v[112:115], v[164:167], v[204:207], v[112:115]
	v_mfma_f32_16x16x32_bf16 v[104:107], v[140:143], v[208:211], v[104:107]
	v_mfma_f32_16x16x32_bf16 v[104:107], v[148:151], v[212:215], v[104:107]
	v_mfma_f32_16x16x32_bf16 v[96:99], v[152:155], v[208:211], v[96:99]
	v_mfma_f32_16x16x32_bf16 v[96:99], v[164:167], v[212:215], v[96:99]
	v_mfma_f32_16x16x32_bf16 v[88:91], v[140:143], v[216:219], v[88:91]
	v_mfma_f32_16x16x32_bf16 v[88:91], v[148:151], v[220:223], v[88:91]
	v_mfma_f32_16x16x32_bf16 v[80:83], v[152:155], v[216:219], v[80:83]
	v_mfma_f32_16x16x32_bf16 v[80:83], v[164:167], v[220:223], v[80:83]
	s_setprio 0
	s_setprio 1
	v_mfma_f32_16x16x32_bf16 v[116:119], v[168:171], v[184:187], v[116:119]
	v_mfma_f32_16x16x32_bf16 v[116:119], v[172:175], v[188:191], v[116:119]
	v_mfma_f32_16x16x32_bf16 v[108:111], v[176:179], v[184:187], v[108:111]
	v_mfma_f32_16x16x32_bf16 v[108:111], v[180:183], v[188:191], v[108:111]
	v_mfma_f32_16x16x32_bf16 v[100:103], v[168:171], v[192:195], v[100:103]
	v_mfma_f32_16x16x32_bf16 v[100:103], v[172:175], v[204:207], v[100:103]
	v_mfma_f32_16x16x32_bf16 v[92:95], v[176:179], v[192:195], v[92:95]
	v_mfma_f32_16x16x32_bf16 v[92:95], v[180:183], v[204:207], v[92:95]
	v_mfma_f32_16x16x32_bf16 v[84:87], v[168:171], v[208:211], v[84:87]
	v_mfma_f32_16x16x32_bf16 v[84:87], v[172:175], v[212:215], v[84:87]
	v_mfma_f32_16x16x32_bf16 v[76:79], v[176:179], v[208:211], v[76:79]
	v_mfma_f32_16x16x32_bf16 v[76:79], v[180:183], v[212:215], v[76:79]
	v_mfma_f32_16x16x32_bf16 v[72:75], v[168:171], v[216:219], v[72:75]
	v_mfma_f32_16x16x32_bf16 v[72:75], v[172:175], v[220:223], v[72:75]
	s_setprio 2
	s_barrier
; #define PG8_STAGE(bufoff, gbase, voff) do { _Pragma("unroll") for (int _i = 0; _i < 2; ++_i) \
;         __builtin_amdgcn_global_load_lds((const unsigned*)((const char*)(gbase) + (voff)[_i]), (LAS unsigned*)(lds + (bufoff) + ldsw + _i * 8192), 16, 0, 0); } while (0)
; #define PG8_LDA(dst, b, h) do { _Pragma("unroll") for (int m = 0; m < 4; ++m) _Pragma("unroll") for (int k = 0; k < 2; ++k) dst[m][k] = *(const LAS bf16x8*)(lds + PG8_SA(b, h) + aoff + m * 2048 + k * 1024); } while (0)
; #define PG8_MMA(ai, bj, At, Bt) do { __builtin_amdgcn_s_setprio(1); _Pragma("unroll") for (int m = 0; m < 4; ++m) _Pragma("unroll") for (int n = 0; n < 2; ++n) _Pragma("unroll") for (int k = 0; k < 2; ++k) \
;         acc[ai][bj][m][n] = __builtin_amdgcn_mfma_f32_16x16x32_bf16(Bt[n][k], At[m][k], acc[ai][bj][m][n], 0, 0, 0); __builtin_amdgcn_s_setprio(0); } while (0)
; #define PG8_WAIT_V(n) asm volatile("s_waitcnt vmcnt(" #n ")" ::: "memory")
; #define PG8_WAIT_L(n) asm volatile("s_waitcnt lgkmcnt(" #n ")" ::: "memory")
; #define PG8_BAR __builtin_amdgcn_s_barrier()
; #define PG8_SCHED __builtin_amdgcn_sched_barrier(0)
; template <class Epi, class Sched, bool ALIGN_EPI = true>
; __device__ __forceinline__ void gemm_phase(LAS unsigned char* lds, const Gemm g, const Sched& S, const Epi& E) {
;     ...
;             const bool last = (t == nt - 2);
;             const char* a1 = cA + (size_t)(t + 1) * kstep;
;             const char* a2 = last ? nA : cA + (size_t)(t + 2) * kstep; const char* b2 = last ? nB : cB + (size_t)(t + 2) * kstep;
;             const char* a3 = a2 + kstep; const char* b3 = b2 + kstep;
;     ...
;             PG8_LDA(At, 1, 1); PG8_STAGE(PG8_SB(1, 0), b3, voffB); PG8_STAGE(PG8_SB(1, 1), b3 + hB, voffB); PG8_STAGE(PG8_SA(1, 0), a3, voffA);
;             PG8_WAIT_V(8); PG8_WAIT_L(0); PG8_BAR; PG8_MMA(1, 0, At, B0); PG8_MMA(1, 1, At, B1); PG8_BAR; PG8_SCHED;
;         }
	v_mfma_f32_16x16x32_bf16 v[68:71], v[176:179], v[216:219], v[68:71]
	v_mfma_f32_16x16x32_bf16 v[68:71], v[180:183], v[220:223], v[68:71]
	s_setprio 0
	s_add_i32 s27, s27, s53
	v_lshl_add_u64 v[156:157], v[156:157], 0, s[86:87]
	s_mov_b32 m0, s27
	ds_read_b128 v[184:187], v147 offset:49152
	ds_read_b128 v[188:191], v147 offset:50176
	ds_read_b128 v[192:195], v147 offset:51200
	ds_read_b128 v[204:207], v147 offset:52224
	ds_read_b128 v[208:211], v147 offset:53248
	ds_read_b128 v[212:215], v147 offset:54272
	ds_read_b128 v[216:219], v147 offset:55296
	ds_read_b128 v[220:223], v147 offset:56320
	global_load_lds_dwordx4 v[156:157], off
	s_add_i32 m0, s27, 0x2000
	s_add_u32 s30, s40, 0x80080
	v_lshl_add_u64 v[156:157], v[196:197], 0, s[86:87]
	s_addc_u32 s31, s41, 0
	s_add_i32 s27, s65, s53
	global_load_lds_dwordx4 v[156:157], off
	v_lshl_add_u64 v[156:157], s[30:31], 0, v[2:3]
	s_mov_b32 m0, s27
	s_nop 0
	global_load_lds_dwordx4 v[156:157], off
	v_lshl_add_u64 v[156:157], s[30:31], 0, v[0:1]
	s_add_i32 m0, s27, 0x2000
	s_nop 0
	global_load_lds_dwordx4 v[156:157], off
	v_lshl_add_u64 v[156:157], v[224:225], 0, s[86:87]
	s_mov_b32 m0, s62
	s_nop 0
	global_load_lds_dwordx4 v[156:157], off
	v_lshl_add_u64 v[156:157], v[226:227], 0, s[86:87]
	s_mov_b32 m0, s63
	s_nop 0
	global_load_lds_dwordx4 v[156:157], off
	s_add_i32 s26, s26, 2
	s_add_u32 s38, s38, 0x100
	s_addc_u32 s39, s39, 0
	s_add_u32 s24, s24, 0x100
	s_addc_u32 s25, s25, 0
	s_add_u32 s27, s38, 0xfff80080
	s_addc_u32 s30, s39, -1
	s_add_i32 s31, 0, 0x10000
	s_cmp_eq_u32 s26, 28
	s_cselect_b32 s43, s11, s30
	s_cselect_b32 s42, s18, s27
	s_cselect_b32 s41, s9, s25
	s_cselect_b32 s40, s19, s24
	s_add_i32 s27, 0, 0x14000
	s_waitcnt vmcnt(8)
	s_waitcnt lgkmcnt(0)
	s_barrier
	s_setprio 1
	s_waitcnt lgkmcnt(0)
	v_mfma_f32_16x16x32_bf16 v[64:67], v[140:143], v[184:187], v[64:67]
	v_mfma_f32_16x16x32_bf16 v[64:67], v[148:151], v[188:191], v[64:67]
	v_mfma_f32_16x16x32_bf16 v[60:63], v[152:155], v[184:187], v[60:63]
	v_mfma_f32_16x16x32_bf16 v[60:63], v[164:167], v[188:191], v[60:63]
	v_mfma_f32_16x16x32_bf16 v[56:59], v[140:143], v[192:195], v[56:59]
	v_mfma_f32_16x16x32_bf16 v[56:59], v[148:151], v[204:207], v[56:59]
	v_mfma_f32_16x16x32_bf16 v[48:51], v[152:155], v[192:195], v[48:51]
	v_mfma_f32_16x16x32_bf16 v[48:51], v[164:167], v[204:207], v[48:51]
	v_mfma_f32_16x16x32_bf16 v[40:43], v[140:143], v[208:211], v[40:43]
	v_mfma_f32_16x16x32_bf16 v[40:43], v[148:151], v[212:215], v[40:43]
	v_mfma_f32_16x16x32_bf16 v[32:35], v[152:155], v[208:211], v[32:35]
	v_mfma_f32_16x16x32_bf16 v[32:35], v[164:167], v[212:215], v[32:35]
	v_mfma_f32_16x16x32_bf16 v[24:27], v[140:143], v[216:219], v[24:27]
	v_mfma_f32_16x16x32_bf16 v[24:27], v[148:151], v[220:223], v[24:27]
	v_mfma_f32_16x16x32_bf16 v[16:19], v[152:155], v[216:219], v[16:19]
	v_mfma_f32_16x16x32_bf16 v[16:19], v[164:167], v[220:223], v[16:19]
	s_setprio 0
	s_setprio 1
	v_mfma_f32_16x16x32_bf16 v[52:55], v[168:171], v[184:187], v[52:55]
	v_mfma_f32_16x16x32_bf16 v[52:55], v[172:175], v[188:191], v[52:55]
	v_mfma_f32_16x16x32_bf16 v[44:47], v[176:179], v[184:187], v[44:47]
	v_mfma_f32_16x16x32_bf16 v[44:47], v[180:183], v[188:191], v[44:47]
	v_mfma_f32_16x16x32_bf16 v[36:39], v[168:171], v[192:195], v[36:39]
	v_mfma_f32_16x16x32_bf16 v[36:39], v[172:175], v[204:207], v[36:39]
	v_mfma_f32_16x16x32_bf16 v[28:31], v[176:179], v[192:195], v[28:31]
	v_mfma_f32_16x16x32_bf16 v[28:31], v[180:183], v[204:207], v[28:31]
	v_mfma_f32_16x16x32_bf16 v[20:23], v[168:171], v[208:211], v[20:23]
	v_mfma_f32_16x16x32_bf16 v[20:23], v[172:175], v[212:215], v[20:23]
	v_mfma_f32_16x16x32_bf16 v[12:15], v[176:179], v[208:211], v[12:15]
	v_mfma_f32_16x16x32_bf16 v[12:15], v[180:183], v[212:215], v[12:15]
	v_mfma_f32_16x16x32_bf16 v[8:11], v[168:171], v[216:219], v[8:11]
	v_mfma_f32_16x16x32_bf16 v[8:11], v[172:175], v[220:223], v[8:11]
	s_setprio 2
	s_barrier
	v_mfma_f32_16x16x32_bf16 v[4:7], v[176:179], v[216:219], v[4:7]
	v_mfma_f32_16x16x32_bf16 v[4:7], v[180:183], v[220:223], v[4:7]
	s_setprio 0
	s_cmp_gt_u32 s26, 29
	s_cbranch_scc0 .LBB0_218

; #define PG8_WAIT_V(n) asm volatile("s_waitcnt vmcnt(" #n ")" ::: "memory")
; #define PG8_BAR __builtin_amdgcn_s_barrier()
;     __device__ __forceinline__ void operator()(f32x4 (&acc)[2][2][4][2], const Unit& u, int wr, int wc, int fr_, int fq_, int wid, int lane_) const {
;     ...
;             const int t = wid * 64 + lane, kind = t >> 6, pr = t & 63, bj = kind >> 2, tap = kind & 3;
;             const float* src = (tap < 3) ? (cw + (size_t)tap * FF2 + bj * FF + u.pn * 128 + 2 * pr) : (cb + bj * FF + u.pn * 128 + 2 * pr);
;             const f32x2 wv = *(const f32x2*)src;
; template <class Epi, class Sched, bool ALIGN_EPI = true>
; __device__ __forceinline__ void gemm_phase(LAS unsigned char* lds, const Gemm g, const Sched& S, const Epi& E) {
;     ...
;         const bool has_next = S.next(ui + 1, nxt);
;         const char* nA = has_next ? (const char*)g.A + ((size_t)nxt.pm * BM * g.lda + (size_t)nxt.pn * g.a_pn_off) * 2 : cA; const char* nB = has_next ? (const char*)g.Bt + (size_t)nxt.pn * BM * g.ldb * 2 : cB;
;         for (int t = 0; t < nt; t += 2) {
;             const bool last = (t == nt - 2);
;             const char* a1 = cA + (size_t)(t + 1) * kstep;
;             const char* a2 = last ? nA : cA + (size_t)(t + 2) * kstep; const char* b2 = last ? nB : cB + (size_t)(t + 2) * kstep;
;             const char* a3 = a2 + kstep; const char* b3 = b2 + kstep;
;             PG8_LDB(B0, 0, 0); PG8_LDB(B1, 0, 1); PG8_SCHED; PG8_LDA(At, 0, 0); PG8_STAGE(PG8_SA(1, 1), a1 + hA, voffA);
;             PG8_WAIT_V(8); PG8_WAIT_L(0); PG8_BAR; PG8_MMA(0, 0, At, B0); PG8_MMA(0, 1, At, B1); PG8_BAR; PG8_SCHED;
;             PG8_LDA(At, 0, 1); PG8_STAGE(PG8_SB(0, 0), b2, voffB); PG8_STAGE(PG8_SB(0, 1), b2 + hB, voffB); PG8_STAGE(PG8_SA(0, 0), a2, voffA);
;             PG8_WAIT_V(8); PG8_WAIT_L(0); PG8_BAR; PG8_MMA(1, 0, At, B0); PG8_MMA(1, 1, At, B1); PG8_BAR; PG8_SCHED;
;             PG8_LDB(B0, 1, 0); PG8_LDB(B1, 1, 1); PG8_SCHED; PG8_LDA(At, 1, 0); PG8_STAGE(PG8_SA(0, 1), a2 + hA, voffA);
;             PG8_WAIT_V(8); PG8_WAIT_L(0); PG8_BAR; PG8_MMA(0, 0, At, B0); PG8_MMA(0, 1, At, B1); PG8_BAR; PG8_SCHED;
;             PG8_LDA(At, 1, 1); PG8_STAGE(PG8_SB(1, 0), b3, voffB); PG8_STAGE(PG8_SB(1, 1), b3 + hB, voffB); PG8_STAGE(PG8_SA(1, 0), a3, voffA);
;             PG8_WAIT_V(8); PG8_WAIT_L(0); PG8_BAR; PG8_MMA(1, 0, At, B0); PG8_MMA(1, 1, At, B1); PG8_BAR; PG8_SCHED;
.LBB0_827:
	s_ashr_i32 s39, s38, 31
	s_lshl_b64 s[16:17], s[38:39], 20
	s_add_u32 s40, s46, s16
	s_addc_u32 s41, s47, s17
	s_and_b64 s[16:17], s[4:5], exec
	s_cselect_b32 s16, s41, s7
	s_cselect_b32 s17, s40, s6
	s_ashr_i32 s15, s14, 31
	s_lshl_b64 s[18:19], s[14:15], 20
	s_add_u32 s42, s53, s18
	s_addc_u32 s43, s60, s19
	s_and_b64 s[18:19], s[4:5], exec
	s_cselect_b32 s15, s43, s45
	s_cselect_b32 s18, s42, s44
	s_add_u32 s6, s6, 0x80080
	s_addc_u32 s7, s7, 0
	s_add_u32 s19, s44, 0x100
	s_addc_u32 s24, s45, 0
	s_mov_b32 s25, -2
	v_add_u32_e32 v228, s77, v158
	v_ashrrev_i32_e32 v229, 6, v228
	v_and_b32_e32 v230, 3, v229
	v_lshrrev_b32_e32 v231, 8, v228
	v_mul_u32_u24_e32 v228, 0x2c00, v230
	v_lshlrev_b32_e32 v228, 2, v228
	v_mov_b32_e32 v229, 0
	v_lshl_add_u64 v[232:233], s[2:3], 0, v[228:229]
	v_mov_b32_e32 v228, s9
	v_cmp_eq_u32_e32 vcc, 3, v230
	v_mul_i32_i24_e32 v234, 0x1600, v231
	v_ashrrev_i32_e32 v235, 31, v234
	v_cndmask_b32_e32 v233, v233, v228, vcc
	v_mov_b32_e32 v228, s8
	v_cndmask_b32_e32 v232, v232, v228, vcc
	v_lshl_add_u64 v[232:233], v[234:235], 2, v[232:233]
	s_lshl_b32 s26, s82, 7
	s_ashr_i32 s27, s26, 31
	v_lshl_add_u64 v[232:233], s[26:27], 2, v[232:233]
	v_and_b32_e32 v228, 63, v158
	v_lshlrev_b32_e32 v228, 3, v228
	v_mov_b32_e32 v229, 0
	v_lshl_add_u64 v[232:233], v[232:233], 0, v[228:229]
	global_load_dwordx2 v[226:227], v[232:233], off
	s_add_u32 s26, s6, 0xfff80080
	s_addc_u32 s27, s7, -1
	s_add_i32 s30, 0, 0x10000
	s_cmp_eq_u32 s25, 28
	s_cselect_b32 s59, s16, s27
	s_cselect_b32 s58, s17, s26
	v_add_u32_e32 v2, s30, v204
	s_cselect_b32 s45, s15, s24
	s_cselect_b32 s44, s18, s19
	s_add_i32 s31, 0, 0x14000
	ds_read_b128 v[132:135], v2
	ds_read_b128 v[136:139], v2 offset:1024
	ds_read_b128 v[140:143], v2 offset:2048
	ds_read_b128 v[144:147], v2 offset:3072
	v_add_u32_e32 v2, s31, v204
	ds_read_b128 v[148:151], v2
	ds_read_b128 v[152:155], v2 offset:1024
	ds_read_b128 v[174:177], v2 offset:2048
	ds_read_b128 v[178:181], v2 offset:3072
	v_lshl_add_u64 v[156:157], s[6:7], 0, v[170:171]
	s_add_i32 m0, s62, 0xc000
	ds_read_b128 v[182:185], v205
	ds_read_b128 v[186:189], v205 offset:1024
	ds_read_b128 v[190:193], v205 offset:2048
	ds_read_b128 v[194:197], v205 offset:3072
	ds_read_b128 v[206:209], v205 offset:4096
	ds_read_b128 v[210:213], v205 offset:5120
	ds_read_b128 v[214:217], v205 offset:6144
	ds_read_b128 v[218:221], v205 offset:7168
	global_load_lds_dwordx4 v[156:157], off
	v_lshl_add_u64 v[156:157], s[6:7], 0, v[172:173]
	s_add_i32 m0, s62, 0xe000
	s_nop 0
	global_load_lds_dwordx4 v[156:157], off
	s_waitcnt vmcnt(8)
	s_waitcnt lgkmcnt(0)
	s_barrier
	s_setprio 1
	s_waitcnt lgkmcnt(0)
	v_mfma_f32_16x16x32_bf16 v[116:119], v[132:135], v[182:185], 0
	v_mfma_f32_16x16x32_bf16 v[116:119], v[136:139], v[186:189], v[116:119]
	v_mfma_f32_16x16x32_bf16 v[100:103], v[140:143], v[182:185], 0
	v_mfma_f32_16x16x32_bf16 v[100:103], v[144:147], v[186:189], v[100:103]
	v_mfma_f32_16x16x32_bf16 v[108:111], v[132:135], v[190:193], 0
	v_mfma_f32_16x16x32_bf16 v[108:111], v[136:139], v[194:197], v[108:111]
	v_mfma_f32_16x16x32_bf16 v[96:99], v[140:143], v[190:193], 0
	v_mfma_f32_16x16x32_bf16 v[96:99], v[144:147], v[194:197], v[96:99]
	v_mfma_f32_16x16x32_bf16 v[88:91], v[132:135], v[206:209], 0
	v_mfma_f32_16x16x32_bf16 v[88:91], v[136:139], v[210:213], v[88:91]
	v_mfma_f32_16x16x32_bf16 v[84:87], v[140:143], v[206:209], 0
	v_mfma_f32_16x16x32_bf16 v[84:87], v[144:147], v[210:213], v[84:87]
	v_mfma_f32_16x16x32_bf16 v[72:75], v[132:135], v[214:217], 0
	v_mfma_f32_16x16x32_bf16 v[72:75], v[136:139], v[218:221], v[72:75]
	v_mfma_f32_16x16x32_bf16 v[80:83], v[140:143], v[214:217], 0
	v_mfma_f32_16x16x32_bf16 v[80:83], v[144:147], v[218:221], v[80:83]
	s_setprio 0
	s_setprio 1
	v_mfma_f32_16x16x32_bf16 v[128:131], v[148:151], v[182:185], 0
	v_mfma_f32_16x16x32_bf16 v[128:131], v[152:155], v[186:189], v[128:131]
	v_mfma_f32_16x16x32_bf16 v[44:47], v[174:177], v[182:185], 0
	v_mfma_f32_16x16x32_bf16 v[44:47], v[178:181], v[186:189], v[44:47]
	v_mfma_f32_16x16x32_bf16 v[124:127], v[148:151], v[190:193], 0
	v_mfma_f32_16x16x32_bf16 v[124:127], v[152:155], v[194:197], v[124:127]
	v_mfma_f32_16x16x32_bf16 v[36:39], v[174:177], v[190:193], 0
	v_mfma_f32_16x16x32_bf16 v[36:39], v[178:181], v[194:197], v[36:39]
	v_mfma_f32_16x16x32_bf16 v[120:123], v[148:151], v[206:209], 0
	v_mfma_f32_16x16x32_bf16 v[120:123], v[152:155], v[210:213], v[120:123]
	v_mfma_f32_16x16x32_bf16 v[32:35], v[174:177], v[206:209], 0
	v_mfma_f32_16x16x32_bf16 v[32:35], v[178:181], v[210:213], v[32:35]
	v_mfma_f32_16x16x32_bf16 v[112:115], v[148:151], v[214:217], 0
	v_mfma_f32_16x16x32_bf16 v[112:115], v[152:155], v[218:221], v[112:115]
	s_setprio 2
	s_barrier
	v_mfma_f32_16x16x32_bf16 v[28:31], v[174:177], v[214:217], 0
	v_mfma_f32_16x16x32_bf16 v[28:31], v[178:181], v[218:221], v[28:31]
	s_setprio 0
	s_add_i32 s26, s30, s61
	v_lshl_add_u64 v[156:157], s[44:45], 0, v[166:167]
	s_mov_b32 m0, s26
	ds_read_b128 v[182:185], v205 offset:16384
	ds_read_b128 v[186:189], v205 offset:17408
	ds_read_b128 v[190:193], v205 offset:18432
	ds_read_b128 v[194:197], v205 offset:19456
	ds_read_b128 v[206:209], v205 offset:20480
	ds_read_b128 v[210:213], v205 offset:21504
	ds_read_b128 v[214:217], v205 offset:22528
	ds_read_b128 v[218:221], v205 offset:23552
	global_load_lds_dwordx4 v[156:157], off
	s_add_i32 m0, s26, 0x2000
	s_add_u32 s26, s44, 0x80000
	v_lshl_add_u64 v[160:161], s[44:45], 0, v[0:1]
	s_addc_u32 s27, s45, 0
	s_add_i32 s30, s31, s61
	global_load_lds_dwordx4 v[160:161], off
	v_lshl_add_u64 v[162:163], s[26:27], 0, v[166:167]
	s_mov_b32 m0, s30
	v_lshl_add_u64 v[222:223], s[58:59], 0, v[164:165]
	global_load_lds_dwordx4 v[162:163], off
	v_lshl_add_u64 v[162:163], s[26:27], 0, v[0:1]
	s_add_i32 m0, s30, 0x2000
	s_nop 0
	global_load_lds_dwordx4 v[162:163], off
	v_lshl_add_u64 v[162:163], s[58:59], 0, v[168:169]
	s_mov_b32 m0, s62
	s_nop 0
	global_load_lds_dwordx4 v[162:163], off
	s_mov_b32 m0, s63
	s_nop 0
	global_load_lds_dwordx4 v[222:223], off
	s_waitcnt vmcnt(8)
	s_waitcnt lgkmcnt(0)
	s_barrier
; #define PG8_STAGE(bufoff, gbase, voff) do { _Pragma("unroll") for (int _i = 0; _i < 2; ++_i) \
;         __builtin_amdgcn_global_load_lds((const unsigned*)((const char*)(gbase) + (voff)[_i]), (LAS unsigned*)(lds + (bufoff) + ldsw + _i * 8192), 16, 0, 0); } while (0)
; #define PG8_LDA(dst, b, h) do { _Pragma("unroll") for (int m = 0; m < 4; ++m) _Pragma("unroll") for (int k = 0; k < 2; ++k) dst[m][k] = *(const LAS bf16x8*)(lds + PG8_SA(b, h) + aoff + m * 2048 + k * 1024); } while (0)
; #define PG8_LDB(dst, b, h) do { _Pragma("unroll") for (int n = 0; n < 2; ++n) _Pragma("unroll") for (int k = 0; k < 2; ++k) dst[n][k] = *(const LAS bf16x8*)(lds + PG8_SB(b, h) + boff + n * 2048 + k * 1024); } while (0)
; #define PG8_MMA(ai, bj, At, Bt) do { __builtin_amdgcn_s_setprio(1); _Pragma("unroll") for (int m = 0; m < 4; ++m) _Pragma("unroll") for (int n = 0; n < 2; ++n) _Pragma("unroll") for (int k = 0; k < 2; ++k) \
;         acc[ai][bj][m][n] = __builtin_amdgcn_mfma_f32_16x16x32_bf16(Bt[n][k], At[m][k], acc[ai][bj][m][n], 0, 0, 0); __builtin_amdgcn_s_setprio(0); } while (0)
; #define PG8_WAIT_V(n) asm volatile("s_waitcnt vmcnt(" #n ")" ::: "memory")
; #define PG8_WAIT_L(n) asm volatile("s_waitcnt lgkmcnt(" #n ")" ::: "memory")
; #define PG8_BAR __builtin_amdgcn_s_barrier()
; #define PG8_SCHED __builtin_amdgcn_sched_barrier(0)
; template <class Epi, class Sched, bool ALIGN_EPI = true>
; __device__ __forceinline__ void gemm_phase(LAS unsigned char* lds, const Gemm g, const Sched& S, const Epi& E) {
;     ...
;             PG8_LDA(At, 0, 1); PG8_STAGE(PG8_SB(0, 0), b2, voffB); PG8_STAGE(PG8_SB(0, 1), b2 + hB, voffB); PG8_STAGE(PG8_SA(0, 0), a2, voffA);
;             PG8_WAIT_V(8); PG8_WAIT_L(0); PG8_BAR; PG8_MMA(1, 0, At, B0); PG8_MMA(1, 1, At, B1); PG8_BAR; PG8_SCHED;
;             PG8_LDB(B0, 1, 0); PG8_LDB(B1, 1, 1); PG8_SCHED; PG8_LDA(At, 1, 0); PG8_STAGE(PG8_SA(0, 1), a2 + hA, voffA);
;             PG8_WAIT_V(8); PG8_WAIT_L(0); PG8_BAR; PG8_MMA(0, 0, At, B0); PG8_MMA(0, 1, At, B1); PG8_BAR; PG8_SCHED;
	s_setprio 1
	s_waitcnt lgkmcnt(0)
	v_mfma_f32_16x16x32_bf16 v[60:63], v[132:135], v[182:185], 0
	v_mfma_f32_16x16x32_bf16 v[60:63], v[136:139], v[186:189], v[60:63]
	v_mfma_f32_16x16x32_bf16 v[68:71], v[140:143], v[182:185], 0
	v_mfma_f32_16x16x32_bf16 v[68:71], v[144:147], v[186:189], v[68:71]
	v_mfma_f32_16x16x32_bf16 v[40:43], v[132:135], v[190:193], 0
	v_mfma_f32_16x16x32_bf16 v[40:43], v[136:139], v[194:197], v[40:43]
	v_mfma_f32_16x16x32_bf16 v[64:67], v[140:143], v[190:193], 0
	v_mfma_f32_16x16x32_bf16 v[64:67], v[144:147], v[194:197], v[64:67]
	v_mfma_f32_16x16x32_bf16 v[24:27], v[132:135], v[206:209], 0
	v_mfma_f32_16x16x32_bf16 v[24:27], v[136:139], v[210:213], v[24:27]
	v_mfma_f32_16x16x32_bf16 v[56:59], v[140:143], v[206:209], 0
	v_mfma_f32_16x16x32_bf16 v[56:59], v[144:147], v[210:213], v[56:59]
	v_mfma_f32_16x16x32_bf16 v[12:15], v[132:135], v[214:217], 0
	v_mfma_f32_16x16x32_bf16 v[12:15], v[136:139], v[218:221], v[12:15]
	v_mfma_f32_16x16x32_bf16 v[48:51], v[140:143], v[214:217], 0
	v_mfma_f32_16x16x32_bf16 v[48:51], v[144:147], v[218:221], v[48:51]
	s_setprio 0
	s_setprio 1
	v_mfma_f32_16x16x32_bf16 v[104:107], v[148:151], v[182:185], 0
	v_mfma_f32_16x16x32_bf16 v[104:107], v[152:155], v[186:189], v[104:107]
	v_mfma_f32_16x16x32_bf16 v[20:23], v[174:177], v[182:185], 0
	v_mfma_f32_16x16x32_bf16 v[20:23], v[178:181], v[186:189], v[20:23]
	v_mfma_f32_16x16x32_bf16 v[92:95], v[148:151], v[190:193], 0
	v_mfma_f32_16x16x32_bf16 v[92:95], v[152:155], v[194:197], v[92:95]
	v_mfma_f32_16x16x32_bf16 v[16:19], v[174:177], v[190:193], 0
	v_mfma_f32_16x16x32_bf16 v[16:19], v[178:181], v[194:197], v[16:19]
	v_mfma_f32_16x16x32_bf16 v[76:79], v[148:151], v[206:209], 0
	v_mfma_f32_16x16x32_bf16 v[76:79], v[152:155], v[210:213], v[76:79]
	v_mfma_f32_16x16x32_bf16 v[8:11], v[174:177], v[206:209], 0
	v_mfma_f32_16x16x32_bf16 v[8:11], v[178:181], v[210:213], v[8:11]
	v_mfma_f32_16x16x32_bf16 v[52:55], v[148:151], v[214:217], 0
	v_mfma_f32_16x16x32_bf16 v[52:55], v[152:155], v[218:221], v[52:55]
	s_setprio 2
	s_barrier
	v_mfma_f32_16x16x32_bf16 v[4:7], v[174:177], v[214:217], 0
	v_mfma_f32_16x16x32_bf16 v[4:7], v[178:181], v[218:221], v[4:7]
	s_setprio 0
	s_add_i32 s30, 0, 0x18000
	v_add_u32_e32 v2, s30, v204
	s_add_i32 s31, 0, 0x1c000
	ds_read_b128 v[132:135], v2
	ds_read_b128 v[136:139], v2 offset:1024
	ds_read_b128 v[140:143], v2 offset:2048
	ds_read_b128 v[144:147], v2 offset:3072
	v_add_u32_e32 v2, s31, v204
	ds_read_b128 v[148:151], v2
	ds_read_b128 v[152:155], v2 offset:1024
	ds_read_b128 v[174:177], v2 offset:2048
	ds_read_b128 v[178:181], v2 offset:3072
	s_add_u32 s26, s58, 0x80000
	s_addc_u32 s27, s59, 0
	s_mov_b32 m0, s64
	v_lshl_add_u64 v[224:225], s[26:27], 0, v[168:169]
	ds_read_b128 v[182:185], v205 offset:32768
	ds_read_b128 v[186:189], v205 offset:33792
	ds_read_b128 v[190:193], v205 offset:34816
	ds_read_b128 v[194:197], v205 offset:35840
	ds_read_b128 v[206:209], v205 offset:36864
	ds_read_b128 v[210:213], v205 offset:37888
	ds_read_b128 v[214:217], v205 offset:38912
	ds_read_b128 v[218:221], v205 offset:39936
	global_load_lds_dwordx4 v[224:225], off
	v_lshl_add_u64 v[224:225], s[26:27], 0, v[164:165]
	s_mov_b32 m0, s65
	s_nop 0
	global_load_lds_dwordx4 v[224:225], off
	s_waitcnt vmcnt(8)
	s_waitcnt lgkmcnt(0)
	s_barrier
	s_setprio 1
	s_waitcnt lgkmcnt(0)
	v_mfma_f32_16x16x32_bf16 v[116:119], v[132:135], v[182:185], v[116:119]
	v_mfma_f32_16x16x32_bf16 v[116:119], v[136:139], v[186:189], v[116:119]
	v_mfma_f32_16x16x32_bf16 v[100:103], v[140:143], v[182:185], v[100:103]
	v_mfma_f32_16x16x32_bf16 v[100:103], v[144:147], v[186:189], v[100:103]
	v_mfma_f32_16x16x32_bf16 v[108:111], v[132:135], v[190:193], v[108:111]
	v_mfma_f32_16x16x32_bf16 v[108:111], v[136:139], v[194:197], v[108:111]
	v_mfma_f32_16x16x32_bf16 v[96:99], v[140:143], v[190:193], v[96:99]
	v_mfma_f32_16x16x32_bf16 v[96:99], v[144:147], v[194:197], v[96:99]
	v_mfma_f32_16x16x32_bf16 v[88:91], v[132:135], v[206:209], v[88:91]
	v_mfma_f32_16x16x32_bf16 v[88:91], v[136:139], v[210:213], v[88:91]
	v_mfma_f32_16x16x32_bf16 v[84:87], v[140:143], v[206:209], v[84:87]
	v_mfma_f32_16x16x32_bf16 v[84:87], v[144:147], v[210:213], v[84:87]
	v_mfma_f32_16x16x32_bf16 v[72:75], v[132:135], v[214:217], v[72:75]
	v_mfma_f32_16x16x32_bf16 v[72:75], v[136:139], v[218:221], v[72:75]
	v_mfma_f32_16x16x32_bf16 v[80:83], v[140:143], v[214:217], v[80:83]
	v_mfma_f32_16x16x32_bf16 v[80:83], v[144:147], v[218:221], v[80:83]
	s_setprio 0
	s_setprio 1
	v_mfma_f32_16x16x32_bf16 v[128:131], v[148:151], v[182:185], v[128:131]
	v_mfma_f32_16x16x32_bf16 v[128:131], v[152:155], v[186:189], v[128:131]
	v_mfma_f32_16x16x32_bf16 v[44:47], v[174:177], v[182:185], v[44:47]
	v_mfma_f32_16x16x32_bf16 v[44:47], v[178:181], v[186:189], v[44:47]
	v_mfma_f32_16x16x32_bf16 v[124:127], v[148:151], v[190:193], v[124:127]
	v_mfma_f32_16x16x32_bf16 v[124:127], v[152:155], v[194:197], v[124:127]
	v_mfma_f32_16x16x32_bf16 v[36:39], v[174:177], v[190:193], v[36:39]
	v_mfma_f32_16x16x32_bf16 v[36:39], v[178:181], v[194:197], v[36:39]
	v_mfma_f32_16x16x32_bf16 v[120:123], v[148:151], v[206:209], v[120:123]
	v_mfma_f32_16x16x32_bf16 v[120:123], v[152:155], v[210:213], v[120:123]
	v_mfma_f32_16x16x32_bf16 v[32:35], v[174:177], v[206:209], v[32:35]
	v_mfma_f32_16x16x32_bf16 v[32:35], v[178:181], v[210:213], v[32:35]
	v_mfma_f32_16x16x32_bf16 v[112:115], v[148:151], v[214:217], v[112:115]
	v_mfma_f32_16x16x32_bf16 v[112:115], v[152:155], v[218:221], v[112:115]
	s_setprio 2
	s_barrier
; #define PG8_STAGE(bufoff, gbase, voff) do { _Pragma("unroll") for (int _i = 0; _i < 2; ++_i) \
;         __builtin_amdgcn_global_load_lds((const unsigned*)((const char*)(gbase) + (voff)[_i]), (LAS unsigned*)(lds + (bufoff) + ldsw + _i * 8192), 16, 0, 0); } while (0)
; #define PG8_LDA(dst, b, h) do { _Pragma("unroll") for (int m = 0; m < 4; ++m) _Pragma("unroll") for (int k = 0; k < 2; ++k) dst[m][k] = *(const LAS bf16x8*)(lds + PG8_SA(b, h) + aoff + m * 2048 + k * 1024); } while (0)
; #define PG8_MMA(ai, bj, At, Bt) do { __builtin_amdgcn_s_setprio(1); _Pragma("unroll") for (int m = 0; m < 4; ++m) _Pragma("unroll") for (int n = 0; n < 2; ++n) _Pragma("unroll") for (int k = 0; k < 2; ++k) \
;         acc[ai][bj][m][n] = __builtin_amdgcn_mfma_f32_16x16x32_bf16(Bt[n][k], At[m][k], acc[ai][bj][m][n], 0, 0, 0); __builtin_amdgcn_s_setprio(0); } while (0)
; #define PG8_WAIT_V(n) asm volatile("s_waitcnt vmcnt(" #n ")" ::: "memory")
; #define PG8_WAIT_L(n) asm volatile("s_waitcnt lgkmcnt(" #n ")" ::: "memory")
; #define PG8_BAR __builtin_amdgcn_s_barrier()
; #define PG8_SCHED __builtin_amdgcn_sched_barrier(0)
; template <class Epi, class Sched, bool ALIGN_EPI = true>
; __device__ __forceinline__ void gemm_phase(LAS unsigned char* lds, const Gemm g, const Sched& S, const Epi& E) {
;     ...
;             const bool last = (t == nt - 2);
;             const char* a1 = cA + (size_t)(t + 1) * kstep;
;             const char* a2 = last ? nA : cA + (size_t)(t + 2) * kstep; const char* b2 = last ? nB : cB + (size_t)(t + 2) * kstep;
;             const char* a3 = a2 + kstep; const char* b3 = b2 + kstep;
;     ...
;             PG8_LDA(At, 1, 1); PG8_STAGE(PG8_SB(1, 0), b3, voffB); PG8_STAGE(PG8_SB(1, 1), b3 + hB, voffB); PG8_STAGE(PG8_SA(1, 0), a3, voffA);
;             PG8_WAIT_V(8); PG8_WAIT_L(0); PG8_BAR; PG8_MMA(1, 0, At, B0); PG8_MMA(1, 1, At, B1); PG8_BAR; PG8_SCHED;
	v_mfma_f32_16x16x32_bf16 v[28:31], v[174:177], v[214:217], v[28:31]
	v_mfma_f32_16x16x32_bf16 v[28:31], v[178:181], v[218:221], v[28:31]
	s_setprio 0
	s_add_i32 s26, s30, s61
	v_lshl_add_u64 v[156:157], v[156:157], 0, s[86:87]
	s_mov_b32 m0, s26
	ds_read_b128 v[182:185], v205 offset:49152
	ds_read_b128 v[186:189], v205 offset:50176
	ds_read_b128 v[190:193], v205 offset:51200
	ds_read_b128 v[194:197], v205 offset:52224
	ds_read_b128 v[206:209], v205 offset:53248
	ds_read_b128 v[210:213], v205 offset:54272
	ds_read_b128 v[214:217], v205 offset:55296
	ds_read_b128 v[218:221], v205 offset:56320
	global_load_lds_dwordx4 v[156:157], off
	s_add_i32 m0, s26, 0x2000
	s_add_u32 s26, s44, 0x80080
	v_lshl_add_u64 v[156:157], v[160:161], 0, s[86:87]
	s_addc_u32 s27, s45, 0
	s_add_i32 s30, s31, s61
	global_load_lds_dwordx4 v[156:157], off
	v_lshl_add_u64 v[156:157], s[26:27], 0, v[166:167]
	s_mov_b32 m0, s30
	s_nop 0
	global_load_lds_dwordx4 v[156:157], off
	v_lshl_add_u64 v[156:157], s[26:27], 0, v[0:1]
	s_add_i32 m0, s30, 0x2000
	s_nop 0
	global_load_lds_dwordx4 v[156:157], off
	v_lshl_add_u64 v[156:157], v[162:163], 0, s[86:87]
	s_mov_b32 m0, s75
	s_nop 0
	global_load_lds_dwordx4 v[156:157], off
	v_lshl_add_u64 v[156:157], v[222:223], 0, s[86:87]
	s_mov_b32 m0, s76
	s_nop 0
	global_load_lds_dwordx4 v[156:157], off
	s_add_i32 s25, s25, 2
	s_add_u32 s6, s6, 0x100
	s_addc_u32 s7, s7, 0
	s_add_u32 s19, s19, 0x100
	s_addc_u32 s24, s24, 0
	s_add_u32 s26, s6, 0xfff80080
	s_addc_u32 s27, s7, -1
	s_add_i32 s30, 0, 0x10000
	s_cmp_eq_u32 s25, 28
	s_cselect_b32 s59, s16, s27
	s_cselect_b32 s58, s17, s26
	s_cselect_b32 s45, s15, s24
	s_cselect_b32 s44, s18, s19
	s_add_i32 s31, 0, 0x14000
	s_waitcnt vmcnt(8)
	s_waitcnt lgkmcnt(0)
	s_barrier
	s_setprio 1
	s_waitcnt lgkmcnt(0)
	v_mfma_f32_16x16x32_bf16 v[60:63], v[132:135], v[182:185], v[60:63]
	v_mfma_f32_16x16x32_bf16 v[60:63], v[136:139], v[186:189], v[60:63]
	v_mfma_f32_16x16x32_bf16 v[68:71], v[140:143], v[182:185], v[68:71]
	v_mfma_f32_16x16x32_bf16 v[68:71], v[144:147], v[186:189], v[68:71]
	v_mfma_f32_16x16x32_bf16 v[40:43], v[132:135], v[190:193], v[40:43]
	v_mfma_f32_16x16x32_bf16 v[40:43], v[136:139], v[194:197], v[40:43]
	v_mfma_f32_16x16x32_bf16 v[64:67], v[140:143], v[190:193], v[64:67]
	v_mfma_f32_16x16x32_bf16 v[64:67], v[144:147], v[194:197], v[64:67]
	v_mfma_f32_16x16x32_bf16 v[24:27], v[132:135], v[206:209], v[24:27]
	v_mfma_f32_16x16x32_bf16 v[24:27], v[136:139], v[210:213], v[24:27]
	v_mfma_f32_16x16x32_bf16 v[56:59], v[140:143], v[206:209], v[56:59]
	v_mfma_f32_16x16x32_bf16 v[56:59], v[144:147], v[210:213], v[56:59]
	v_mfma_f32_16x16x32_bf16 v[12:15], v[132:135], v[214:217], v[12:15]
	v_mfma_f32_16x16x32_bf16 v[12:15], v[136:139], v[218:221], v[12:15]
	v_mfma_f32_16x16x32_bf16 v[48:51], v[140:143], v[214:217], v[48:51]
	v_mfma_f32_16x16x32_bf16 v[48:51], v[144:147], v[218:221], v[48:51]
	s_setprio 0
	s_setprio 1
	v_mfma_f32_16x16x32_bf16 v[104:107], v[148:151], v[182:185], v[104:107]
	v_mfma_f32_16x16x32_bf16 v[104:107], v[152:155], v[186:189], v[104:107]
	v_mfma_f32_16x16x32_bf16 v[20:23], v[174:177], v[182:185], v[20:23]
	v_mfma_f32_16x16x32_bf16 v[20:23], v[178:181], v[186:189], v[20:23]
	v_mfma_f32_16x16x32_bf16 v[92:95], v[148:151], v[190:193], v[92:95]
	v_mfma_f32_16x16x32_bf16 v[92:95], v[152:155], v[194:197], v[92:95]
	v_mfma_f32_16x16x32_bf16 v[16:19], v[174:177], v[190:193], v[16:19]
	v_mfma_f32_16x16x32_bf16 v[16:19], v[178:181], v[194:197], v[16:19]
	v_mfma_f32_16x16x32_bf16 v[76:79], v[148:151], v[206:209], v[76:79]
	v_mfma_f32_16x16x32_bf16 v[76:79], v[152:155], v[210:213], v[76:79]
	v_mfma_f32_16x16x32_bf16 v[8:11], v[174:177], v[206:209], v[8:11]
	v_mfma_f32_16x16x32_bf16 v[8:11], v[178:181], v[210:213], v[8:11]
	v_mfma_f32_16x16x32_bf16 v[52:55], v[148:151], v[214:217], v[52:55]
	v_mfma_f32_16x16x32_bf16 v[52:55], v[152:155], v[218:221], v[52:55]
	s_setprio 2
	s_barrier
	v_mfma_f32_16x16x32_bf16 v[4:7], v[174:177], v[214:217], v[4:7]
	v_mfma_f32_16x16x32_bf16 v[4:7], v[178:181], v[218:221], v[4:7]
	s_setprio 0
	s_cmp_gt_u32 s25, 29
	s_cbranch_scc1 .Lpeel_exit_828
.LBB0_828:
	v_add_u32_e32 v2, s30, v204
	ds_read_b128 v[132:135], v2
	ds_read_b128 v[136:139], v2 offset:1024
	ds_read_b128 v[140:143], v2 offset:2048
	ds_read_b128 v[144:147], v2 offset:3072
	v_add_u32_e32 v2, s31, v204
	ds_read_b128 v[148:151], v2
	ds_read_b128 v[152:155], v2 offset:1024
	ds_read_b128 v[174:177], v2 offset:2048
	ds_read_b128 v[178:181], v2 offset:3072
	v_lshl_add_u64 v[156:157], s[6:7], 0, v[170:171]
	s_add_i32 m0, s62, 0xc000
	ds_read_b128 v[182:185], v205
	ds_read_b128 v[186:189], v205 offset:1024
	ds_read_b128 v[190:193], v205 offset:2048
	ds_read_b128 v[194:197], v205 offset:3072
	ds_read_b128 v[206:209], v205 offset:4096
	ds_read_b128 v[210:213], v205 offset:5120
	ds_read_b128 v[214:217], v205 offset:6144
	ds_read_b128 v[218:221], v205 offset:7168
	global_load_lds_dwordx4 v[156:157], off
	v_lshl_add_u64 v[156:157], s[6:7], 0, v[172:173]
	s_add_i32 m0, s62, 0xe000
	s_nop 0
	global_load_lds_dwordx4 v[156:157], off
	s_waitcnt vmcnt(8)
	s_waitcnt lgkmcnt(0)
	s_barrier
; #define PG8_STAGE(bufoff, gbase, voff) do { _Pragma("unroll") for (int _i = 0; _i < 2; ++_i) \
;         __builtin_amdgcn_global_load_lds((const unsigned*)((const char*)(gbase) + (voff)[_i]), (LAS unsigned*)(lds + (bufoff) + ldsw + _i * 8192), 16, 0, 0); } while (0)
; #define PG8_LDA(dst, b, h) do { _Pragma("unroll") for (int m = 0; m < 4; ++m) _Pragma("unroll") for (int k = 0; k < 2; ++k) dst[m][k] = *(const LAS bf16x8*)(lds + PG8_SA(b, h) + aoff + m * 2048 + k * 1024); } while (0)
; #define PG8_LDB(dst, b, h) do { _Pragma("unroll") for (int n = 0; n < 2; ++n) _Pragma("unroll") for (int k = 0; k < 2; ++k) dst[n][k] = *(const LAS bf16x8*)(lds + PG8_SB(b, h) + boff + n * 2048 + k * 1024); } while (0)
; #define PG8_MMA(ai, bj, At, Bt) do { __builtin_amdgcn_s_setprio(1); _Pragma("unroll") for (int m = 0; m < 4; ++m) _Pragma("unroll") for (int n = 0; n < 2; ++n) _Pragma("unroll") for (int k = 0; k < 2; ++k) \
;         acc[ai][bj][m][n] = __builtin_amdgcn_mfma_f32_16x16x32_bf16(Bt[n][k], At[m][k], acc[ai][bj][m][n], 0, 0, 0); __builtin_amdgcn_s_setprio(0); } while (0)
; #define PG8_WAIT_V(n) asm volatile("s_waitcnt vmcnt(" #n ")" ::: "memory")
; #define PG8_WAIT_L(n) asm volatile("s_waitcnt lgkmcnt(" #n ")" ::: "memory")
; #define PG8_BAR __builtin_amdgcn_s_barrier()
; #define PG8_SCHED __builtin_amdgcn_sched_barrier(0)
; template <class Epi, class Sched, bool ALIGN_EPI = true>
; __device__ __forceinline__ void gemm_phase(LAS unsigned char* lds, const Gemm g, const Sched& S, const Epi& E) {
;     ...
;             PG8_WAIT_V(8); PG8_WAIT_L(0); PG8_BAR; PG8_MMA(0, 0, At, B0); PG8_MMA(0, 1, At, B1); PG8_BAR; PG8_SCHED;
;             PG8_LDA(At, 0, 1); PG8_STAGE(PG8_SB(0, 0), b2, voffB); PG8_STAGE(PG8_SB(0, 1), b2 + hB, voffB); PG8_STAGE(PG8_SA(0, 0), a2, voffA);
;             PG8_WAIT_V(8); PG8_WAIT_L(0); PG8_BAR; PG8_MMA(1, 0, At, B0); PG8_MMA(1, 1, At, B1); PG8_BAR; PG8_SCHED;
;             PG8_LDB(B0, 1, 0); PG8_LDB(B1, 1, 1); PG8_SCHED; PG8_LDA(At, 1, 0); PG8_STAGE(PG8_SA(0, 1), a2 + hA, voffA);
;             PG8_WAIT_V(8); PG8_WAIT_L(0); PG8_BAR; PG8_MMA(0, 0, At, B0); PG8_MMA(0, 1, At, B1); PG8_BAR; PG8_SCHED;
	s_setprio 1
	s_waitcnt lgkmcnt(0)
	v_mfma_f32_16x16x32_bf16 v[116:119], v[132:135], v[182:185], v[116:119]
	v_mfma_f32_16x16x32_bf16 v[116:119], v[136:139], v[186:189], v[116:119]
	v_mfma_f32_16x16x32_bf16 v[100:103], v[140:143], v[182:185], v[100:103]
	v_mfma_f32_16x16x32_bf16 v[100:103], v[144:147], v[186:189], v[100:103]
	v_mfma_f32_16x16x32_bf16 v[108:111], v[132:135], v[190:193], v[108:111]
	v_mfma_f32_16x16x32_bf16 v[108:111], v[136:139], v[194:197], v[108:111]
	v_mfma_f32_16x16x32_bf16 v[96:99], v[140:143], v[190:193], v[96:99]
	v_mfma_f32_16x16x32_bf16 v[96:99], v[144:147], v[194:197], v[96:99]
	v_mfma_f32_16x16x32_bf16 v[88:91], v[132:135], v[206:209], v[88:91]
	v_mfma_f32_16x16x32_bf16 v[88:91], v[136:139], v[210:213], v[88:91]
	v_mfma_f32_16x16x32_bf16 v[84:87], v[140:143], v[206:209], v[84:87]
	v_mfma_f32_16x16x32_bf16 v[84:87], v[144:147], v[210:213], v[84:87]
	v_mfma_f32_16x16x32_bf16 v[72:75], v[132:135], v[214:217], v[72:75]
	v_mfma_f32_16x16x32_bf16 v[72:75], v[136:139], v[218:221], v[72:75]
	v_mfma_f32_16x16x32_bf16 v[80:83], v[140:143], v[214:217], v[80:83]
	v_mfma_f32_16x16x32_bf16 v[80:83], v[144:147], v[218:221], v[80:83]
	s_setprio 0
	s_setprio 1
	v_mfma_f32_16x16x32_bf16 v[128:131], v[148:151], v[182:185], v[128:131]
	v_mfma_f32_16x16x32_bf16 v[128:131], v[152:155], v[186:189], v[128:131]
	v_mfma_f32_16x16x32_bf16 v[44:47], v[174:177], v[182:185], v[44:47]
	v_mfma_f32_16x16x32_bf16 v[44:47], v[178:181], v[186:189], v[44:47]
	v_mfma_f32_16x16x32_bf16 v[124:127], v[148:151], v[190:193], v[124:127]
	v_mfma_f32_16x16x32_bf16 v[124:127], v[152:155], v[194:197], v[124:127]
	v_mfma_f32_16x16x32_bf16 v[36:39], v[174:177], v[190:193], v[36:39]
	v_mfma_f32_16x16x32_bf16 v[36:39], v[178:181], v[194:197], v[36:39]
	v_mfma_f32_16x16x32_bf16 v[120:123], v[148:151], v[206:209], v[120:123]
	v_mfma_f32_16x16x32_bf16 v[120:123], v[152:155], v[210:213], v[120:123]
	v_mfma_f32_16x16x32_bf16 v[32:35], v[174:177], v[206:209], v[32:35]
	v_mfma_f32_16x16x32_bf16 v[32:35], v[178:181], v[210:213], v[32:35]
	v_mfma_f32_16x16x32_bf16 v[112:115], v[148:151], v[214:217], v[112:115]
	v_mfma_f32_16x16x32_bf16 v[112:115], v[152:155], v[218:221], v[112:115]
	s_setprio 2
	s_barrier
	v_mfma_f32_16x16x32_bf16 v[28:31], v[174:177], v[214:217], v[28:31]
	v_mfma_f32_16x16x32_bf16 v[28:31], v[178:181], v[218:221], v[28:31]
	s_setprio 0
	s_add_i32 s26, s30, s61
	v_lshl_add_u64 v[156:157], s[44:45], 0, v[166:167]
	s_mov_b32 m0, s26
	ds_read_b128 v[182:185], v205 offset:16384
	ds_read_b128 v[186:189], v205 offset:17408
	ds_read_b128 v[190:193], v205 offset:18432
	ds_read_b128 v[194:197], v205 offset:19456
	ds_read_b128 v[206:209], v205 offset:20480
	ds_read_b128 v[210:213], v205 offset:21504
	ds_read_b128 v[214:217], v205 offset:22528
	ds_read_b128 v[218:221], v205 offset:23552
	global_load_lds_dwordx4 v[156:157], off
	s_add_i32 m0, s26, 0x2000
	s_add_u32 s26, s44, 0x80000
	v_lshl_add_u64 v[160:161], s[44:45], 0, v[0:1]
	s_addc_u32 s27, s45, 0
	s_add_i32 s30, s31, s61
	global_load_lds_dwordx4 v[160:161], off
	v_lshl_add_u64 v[162:163], s[26:27], 0, v[166:167]
	s_mov_b32 m0, s30
	v_lshl_add_u64 v[222:223], s[58:59], 0, v[164:165]
	global_load_lds_dwordx4 v[162:163], off
	v_lshl_add_u64 v[162:163], s[26:27], 0, v[0:1]
	s_add_i32 m0, s30, 0x2000
	s_nop 0
	global_load_lds_dwordx4 v[162:163], off
	v_lshl_add_u64 v[162:163], s[58:59], 0, v[168:169]
	s_mov_b32 m0, s62
	s_nop 0
	global_load_lds_dwordx4 v[162:163], off
	s_mov_b32 m0, s63
	s_nop 0
	global_load_lds_dwordx4 v[222:223], off
	s_waitcnt vmcnt(8)
	s_waitcnt lgkmcnt(0)
	s_barrier
	s_setprio 1
	s_waitcnt lgkmcnt(0)
	v_mfma_f32_16x16x32_bf16 v[60:63], v[132:135], v[182:185], v[60:63]
	v_mfma_f32_16x16x32_bf16 v[60:63], v[136:139], v[186:189], v[60:63]
	v_mfma_f32_16x16x32_bf16 v[68:71], v[140:143], v[182:185], v[68:71]
	v_mfma_f32_16x16x32_bf16 v[68:71], v[144:147], v[186:189], v[68:71]
	v_mfma_f32_16x16x32_bf16 v[40:43], v[132:135], v[190:193], v[40:43]
	v_mfma_f32_16x16x32_bf16 v[40:43], v[136:139], v[194:197], v[40:43]
	v_mfma_f32_16x16x32_bf16 v[64:67], v[140:143], v[190:193], v[64:67]
	v_mfma_f32_16x16x32_bf16 v[64:67], v[144:147], v[194:197], v[64:67]
	v_mfma_f32_16x16x32_bf16 v[24:27], v[132:135], v[206:209], v[24:27]
	v_mfma_f32_16x16x32_bf16 v[24:27], v[136:139], v[210:213], v[24:27]
	v_mfma_f32_16x16x32_bf16 v[56:59], v[140:143], v[206:209], v[56:59]
	v_mfma_f32_16x16x32_bf16 v[56:59], v[144:147], v[210:213], v[56:59]
	v_mfma_f32_16x16x32_bf16 v[12:15], v[132:135], v[214:217], v[12:15]
	v_mfma_f32_16x16x32_bf16 v[12:15], v[136:139], v[218:221], v[12:15]
	v_mfma_f32_16x16x32_bf16 v[48:51], v[140:143], v[214:217], v[48:51]
	v_mfma_f32_16x16x32_bf16 v[48:51], v[144:147], v[218:221], v[48:51]
	s_setprio 0
	s_setprio 1
	v_mfma_f32_16x16x32_bf16 v[104:107], v[148:151], v[182:185], v[104:107]
	v_mfma_f32_16x16x32_bf16 v[104:107], v[152:155], v[186:189], v[104:107]
	v_mfma_f32_16x16x32_bf16 v[20:23], v[174:177], v[182:185], v[20:23]
	v_mfma_f32_16x16x32_bf16 v[20:23], v[178:181], v[186:189], v[20:23]
	v_mfma_f32_16x16x32_bf16 v[92:95], v[148:151], v[190:193], v[92:95]
	v_mfma_f32_16x16x32_bf16 v[92:95], v[152:155], v[194:197], v[92:95]
	v_mfma_f32_16x16x32_bf16 v[16:19], v[174:177], v[190:193], v[16:19]
	v_mfma_f32_16x16x32_bf16 v[16:19], v[178:181], v[194:197], v[16:19]
	v_mfma_f32_16x16x32_bf16 v[76:79], v[148:151], v[206:209], v[76:79]
	v_mfma_f32_16x16x32_bf16 v[76:79], v[152:155], v[210:213], v[76:79]
	v_mfma_f32_16x16x32_bf16 v[8:11], v[174:177], v[206:209], v[8:11]
	v_mfma_f32_16x16x32_bf16 v[8:11], v[178:181], v[210:213], v[8:11]
	v_mfma_f32_16x16x32_bf16 v[52:55], v[148:151], v[214:217], v[52:55]
	v_mfma_f32_16x16x32_bf16 v[52:55], v[152:155], v[218:221], v[52:55]
	s_setprio 2
	s_barrier
; #define PG8_STAGE(bufoff, gbase, voff) do { _Pragma("unroll") for (int _i = 0; _i < 2; ++_i) \
;         __builtin_amdgcn_global_load_lds((const unsigned*)((const char*)(gbase) + (voff)[_i]), (LAS unsigned*)(lds + (bufoff) + ldsw + _i * 8192), 16, 0, 0); } while (0)
; #define PG8_LDA(dst, b, h) do { _Pragma("unroll") for (int m = 0; m < 4; ++m) _Pragma("unroll") for (int k = 0; k < 2; ++k) dst[m][k] = *(const LAS bf16x8*)(lds + PG8_SA(b, h) + aoff + m * 2048 + k * 1024); } while (0)
; #define PG8_LDB(dst, b, h) do { _Pragma("unroll") for (int n = 0; n < 2; ++n) _Pragma("unroll") for (int k = 0; k < 2; ++k) dst[n][k] = *(const LAS bf16x8*)(lds + PG8_SB(b, h) + boff + n * 2048 + k * 1024); } while (0)
; #define PG8_MMA(ai, bj, At, Bt) do { __builtin_amdgcn_s_setprio(1); _Pragma("unroll") for (int m = 0; m < 4; ++m) _Pragma("unroll") for (int n = 0; n < 2; ++n) _Pragma("unroll") for (int k = 0; k < 2; ++k) \
;         acc[ai][bj][m][n] = __builtin_amdgcn_mfma_f32_16x16x32_bf16(Bt[n][k], At[m][k], acc[ai][bj][m][n], 0, 0, 0); __builtin_amdgcn_s_setprio(0); } while (0)
; #define PG8_WAIT_V(n) asm volatile("s_waitcnt vmcnt(" #n ")" ::: "memory")
; #define PG8_WAIT_L(n) asm volatile("s_waitcnt lgkmcnt(" #n ")" ::: "memory")
; #define PG8_BAR __builtin_amdgcn_s_barrier()
; #define PG8_SCHED __builtin_amdgcn_sched_barrier(0)
; template <class Epi, class Sched, bool ALIGN_EPI = true>
; __device__ __forceinline__ void gemm_phase(LAS unsigned char* lds, const Gemm g, const Sched& S, const Epi& E) {
;     ...
;             PG8_LDB(B0, 1, 0); PG8_LDB(B1, 1, 1); PG8_SCHED; PG8_LDA(At, 1, 0); PG8_STAGE(PG8_SA(0, 1), a2 + hA, voffA);
;             PG8_WAIT_V(8); PG8_WAIT_L(0); PG8_BAR; PG8_MMA(0, 0, At, B0); PG8_MMA(0, 1, At, B1); PG8_BAR; PG8_SCHED;
	v_mfma_f32_16x16x32_bf16 v[4:7], v[174:177], v[214:217], v[4:7]
	v_mfma_f32_16x16x32_bf16 v[4:7], v[178:181], v[218:221], v[4:7]
	s_setprio 0
	s_add_i32 s30, 0, 0x18000
	v_add_u32_e32 v2, s30, v204
	s_add_i32 s31, 0, 0x1c000
	ds_read_b128 v[132:135], v2
	ds_read_b128 v[136:139], v2 offset:1024
	ds_read_b128 v[140:143], v2 offset:2048
	ds_read_b128 v[144:147], v2 offset:3072
	v_add_u32_e32 v2, s31, v204
	ds_read_b128 v[148:151], v2
	ds_read_b128 v[152:155], v2 offset:1024
	ds_read_b128 v[174:177], v2 offset:2048
	ds_read_b128 v[178:181], v2 offset:3072
	s_add_u32 s26, s58, 0x80000
	s_addc_u32 s27, s59, 0
	s_mov_b32 m0, s64
	v_lshl_add_u64 v[224:225], s[26:27], 0, v[168:169]
	ds_read_b128 v[182:185], v205 offset:32768
	ds_read_b128 v[186:189], v205 offset:33792
	ds_read_b128 v[190:193], v205 offset:34816
	ds_read_b128 v[194:197], v205 offset:35840
	ds_read_b128 v[206:209], v205 offset:36864
	ds_read_b128 v[210:213], v205 offset:37888
	ds_read_b128 v[214:217], v205 offset:38912
	ds_read_b128 v[218:221], v205 offset:39936
	global_load_lds_dwordx4 v[224:225], off
	v_lshl_add_u64 v[224:225], s[26:27], 0, v[164:165]
	s_mov_b32 m0, s65
	s_nop 0
	global_load_lds_dwordx4 v[224:225], off
	s_waitcnt vmcnt(8)
	s_waitcnt lgkmcnt(0)
	s_barrier
	s_setprio 1
	s_waitcnt lgkmcnt(0)
	v_mfma_f32_16x16x32_bf16 v[116:119], v[132:135], v[182:185], v[116:119]
	v_mfma_f32_16x16x32_bf16 v[116:119], v[136:139], v[186:189], v[116:119]
	v_mfma_f32_16x16x32_bf16 v[100:103], v[140:143], v[182:185], v[100:103]
	v_mfma_f32_16x16x32_bf16 v[100:103], v[144:147], v[186:189], v[100:103]
	v_mfma_f32_16x16x32_bf16 v[108:111], v[132:135], v[190:193], v[108:111]
	v_mfma_f32_16x16x32_bf16 v[108:111], v[136:139], v[194:197], v[108:111]
	v_mfma_f32_16x16x32_bf16 v[96:99], v[140:143], v[190:193], v[96:99]
	v_mfma_f32_16x16x32_bf16 v[96:99], v[144:147], v[194:197], v[96:99]
	v_mfma_f32_16x16x32_bf16 v[88:91], v[132:135], v[206:209], v[88:91]
	v_mfma_f32_16x16x32_bf16 v[88:91], v[136:139], v[210:213], v[88:91]
	v_mfma_f32_16x16x32_bf16 v[84:87], v[140:143], v[206:209], v[84:87]
	v_mfma_f32_16x16x32_bf16 v[84:87], v[144:147], v[210:213], v[84:87]
	v_mfma_f32_16x16x32_bf16 v[72:75], v[132:135], v[214:217], v[72:75]
	v_mfma_f32_16x16x32_bf16 v[72:75], v[136:139], v[218:221], v[72:75]
	v_mfma_f32_16x16x32_bf16 v[80:83], v[140:143], v[214:217], v[80:83]
	v_mfma_f32_16x16x32_bf16 v[80:83], v[144:147], v[218:221], v[80:83]
	s_setprio 0
	s_setprio 1
	v_mfma_f32_16x16x32_bf16 v[128:131], v[148:151], v[182:185], v[128:131]
	v_mfma_f32_16x16x32_bf16 v[128:131], v[152:155], v[186:189], v[128:131]
	v_mfma_f32_16x16x32_bf16 v[44:47], v[174:177], v[182:185], v[44:47]
	v_mfma_f32_16x16x32_bf16 v[44:47], v[178:181], v[186:189], v[44:47]
	v_mfma_f32_16x16x32_bf16 v[124:127], v[148:151], v[190:193], v[124:127]
	v_mfma_f32_16x16x32_bf16 v[124:127], v[152:155], v[194:197], v[124:127]
	v_mfma_f32_16x16x32_bf16 v[36:39], v[174:177], v[190:193], v[36:39]
	v_mfma_f32_16x16x32_bf16 v[36:39], v[178:181], v[194:197], v[36:39]
	v_mfma_f32_16x16x32_bf16 v[120:123], v[148:151], v[206:209], v[120:123]
	v_mfma_f32_16x16x32_bf16 v[120:123], v[152:155], v[210:213], v[120:123]
	v_mfma_f32_16x16x32_bf16 v[32:35], v[174:177], v[206:209], v[32:35]
	v_mfma_f32_16x16x32_bf16 v[32:35], v[178:181], v[210:213], v[32:35]
	v_mfma_f32_16x16x32_bf16 v[112:115], v[148:151], v[214:217], v[112:115]
	v_mfma_f32_16x16x32_bf16 v[112:115], v[152:155], v[218:221], v[112:115]
	s_setprio 2
	s_barrier
; #define PG8_STAGE(bufoff, gbase, voff) do { _Pragma("unroll") for (int _i = 0; _i < 2; ++_i) \
;         __builtin_amdgcn_global_load_lds((const unsigned*)((const char*)(gbase) + (voff)[_i]), (LAS unsigned*)(lds + (bufoff) + ldsw + _i * 8192), 16, 0, 0); } while (0)
; #define PG8_LDA(dst, b, h) do { _Pragma("unroll") for (int m = 0; m < 4; ++m) _Pragma("unroll") for (int k = 0; k < 2; ++k) dst[m][k] = *(const LAS bf16x8*)(lds + PG8_SA(b, h) + aoff + m * 2048 + k * 1024); } while (0)
; #define PG8_MMA(ai, bj, At, Bt) do { __builtin_amdgcn_s_setprio(1); _Pragma("unroll") for (int m = 0; m < 4; ++m) _Pragma("unroll") for (int n = 0; n < 2; ++n) _Pragma("unroll") for (int k = 0; k < 2; ++k) \
;         acc[ai][bj][m][n] = __builtin_amdgcn_mfma_f32_16x16x32_bf16(Bt[n][k], At[m][k], acc[ai][bj][m][n], 0, 0, 0); __builtin_amdgcn_s_setprio(0); } while (0)
; #define PG8_WAIT_V(n) asm volatile("s_waitcnt vmcnt(" #n ")" ::: "memory")
; #define PG8_WAIT_L(n) asm volatile("s_waitcnt lgkmcnt(" #n ")" ::: "memory")
; #define PG8_BAR __builtin_amdgcn_s_barrier()
; #define PG8_SCHED __builtin_amdgcn_sched_barrier(0)
; template <class Epi, class Sched, bool ALIGN_EPI = true>
; __device__ __forceinline__ void gemm_phase(LAS unsigned char* lds, const Gemm g, const Sched& S, const Epi& E) {
;     ...
;             const bool last = (t == nt - 2);
;             const char* a1 = cA + (size_t)(t + 1) * kstep;
;             const char* a2 = last ? nA : cA + (size_t)(t + 2) * kstep; const char* b2 = last ? nB : cB + (size_t)(t + 2) * kstep;
;             const char* a3 = a2 + kstep; const char* b3 = b2 + kstep;
;     ...
;             PG8_LDA(At, 1, 1); PG8_STAGE(PG8_SB(1, 0), b3, voffB); PG8_STAGE(PG8_SB(1, 1), b3 + hB, voffB); PG8_STAGE(PG8_SA(1, 0), a3, voffA);
;             PG8_WAIT_V(8); PG8_WAIT_L(0); PG8_BAR; PG8_MMA(1, 0, At, B0); PG8_MMA(1, 1, At, B1); PG8_BAR; PG8_SCHED;
;         }
	v_mfma_f32_16x16x32_bf16 v[28:31], v[174:177], v[214:217], v[28:31]
	v_mfma_f32_16x16x32_bf16 v[28:31], v[178:181], v[218:221], v[28:31]
	s_setprio 0
	s_add_i32 s26, s30, s61
	v_lshl_add_u64 v[156:157], v[156:157], 0, s[86:87]
	s_mov_b32 m0, s26
	ds_read_b128 v[182:185], v205 offset:49152
	ds_read_b128 v[186:189], v205 offset:50176
	ds_read_b128 v[190:193], v205 offset:51200
	ds_read_b128 v[194:197], v205 offset:52224
	ds_read_b128 v[206:209], v205 offset:53248
	ds_read_b128 v[210:213], v205 offset:54272
	ds_read_b128 v[214:217], v205 offset:55296
	ds_read_b128 v[218:221], v205 offset:56320
	global_load_lds_dwordx4 v[156:157], off
	s_add_i32 m0, s26, 0x2000
	s_add_u32 s26, s44, 0x80080
	v_lshl_add_u64 v[156:157], v[160:161], 0, s[86:87]
	s_addc_u32 s27, s45, 0
	s_add_i32 s30, s31, s61
	global_load_lds_dwordx4 v[156:157], off
	v_lshl_add_u64 v[156:157], s[26:27], 0, v[166:167]
	s_mov_b32 m0, s30
	s_nop 0
	global_load_lds_dwordx4 v[156:157], off
	v_lshl_add_u64 v[156:157], s[26:27], 0, v[0:1]
	s_add_i32 m0, s30, 0x2000
	s_nop 0
	global_load_lds_dwordx4 v[156:157], off
	v_lshl_add_u64 v[156:157], v[162:163], 0, s[86:87]
	s_mov_b32 m0, s75
	s_nop 0
	global_load_lds_dwordx4 v[156:157], off
	v_lshl_add_u64 v[156:157], v[222:223], 0, s[86:87]
	s_mov_b32 m0, s76
	s_nop 0
	global_load_lds_dwordx4 v[156:157], off
	s_add_i32 s25, s25, 2
	s_add_u32 s6, s6, 0x100
	s_addc_u32 s7, s7, 0
	s_add_u32 s19, s19, 0x100
	s_addc_u32 s24, s24, 0
	s_add_u32 s26, s6, 0xfff80080
	s_addc_u32 s27, s7, -1
	s_add_i32 s30, 0, 0x10000
	s_cmp_eq_u32 s25, 28
	s_cselect_b32 s59, s16, s27
	s_cselect_b32 s58, s17, s26
	s_cselect_b32 s45, s15, s24
	s_cselect_b32 s44, s18, s19
	s_add_i32 s31, 0, 0x14000
	s_waitcnt vmcnt(8)
	s_waitcnt lgkmcnt(0)
	s_barrier
	s_setprio 1
	s_waitcnt lgkmcnt(0)
	v_mfma_f32_16x16x32_bf16 v[60:63], v[132:135], v[182:185], v[60:63]
	v_mfma_f32_16x16x32_bf16 v[60:63], v[136:139], v[186:189], v[60:63]
	v_mfma_f32_16x16x32_bf16 v[68:71], v[140:143], v[182:185], v[68:71]
	v_mfma_f32_16x16x32_bf16 v[68:71], v[144:147], v[186:189], v[68:71]
	v_mfma_f32_16x16x32_bf16 v[40:43], v[132:135], v[190:193], v[40:43]
	v_mfma_f32_16x16x32_bf16 v[40:43], v[136:139], v[194:197], v[40:43]
	v_mfma_f32_16x16x32_bf16 v[64:67], v[140:143], v[190:193], v[64:67]
	v_mfma_f32_16x16x32_bf16 v[64:67], v[144:147], v[194:197], v[64:67]
	v_mfma_f32_16x16x32_bf16 v[24:27], v[132:135], v[206:209], v[24:27]
	v_mfma_f32_16x16x32_bf16 v[24:27], v[136:139], v[210:213], v[24:27]
	v_mfma_f32_16x16x32_bf16 v[56:59], v[140:143], v[206:209], v[56:59]
	v_mfma_f32_16x16x32_bf16 v[56:59], v[144:147], v[210:213], v[56:59]
	v_mfma_f32_16x16x32_bf16 v[12:15], v[132:135], v[214:217], v[12:15]
	v_mfma_f32_16x16x32_bf16 v[12:15], v[136:139], v[218:221], v[12:15]
	v_mfma_f32_16x16x32_bf16 v[48:51], v[140:143], v[214:217], v[48:51]
	v_mfma_f32_16x16x32_bf16 v[48:51], v[144:147], v[218:221], v[48:51]
	s_setprio 0
	s_setprio 1
	v_mfma_f32_16x16x32_bf16 v[104:107], v[148:151], v[182:185], v[104:107]
	v_mfma_f32_16x16x32_bf16 v[104:107], v[152:155], v[186:189], v[104:107]
	v_mfma_f32_16x16x32_bf16 v[20:23], v[174:177], v[182:185], v[20:23]
	v_mfma_f32_16x16x32_bf16 v[20:23], v[178:181], v[186:189], v[20:23]
	v_mfma_f32_16x16x32_bf16 v[92:95], v[148:151], v[190:193], v[92:95]
	v_mfma_f32_16x16x32_bf16 v[92:95], v[152:155], v[194:197], v[92:95]
	v_mfma_f32_16x16x32_bf16 v[16:19], v[174:177], v[190:193], v[16:19]
	v_mfma_f32_16x16x32_bf16 v[16:19], v[178:181], v[194:197], v[16:19]
	v_mfma_f32_16x16x32_bf16 v[76:79], v[148:151], v[206:209], v[76:79]
	v_mfma_f32_16x16x32_bf16 v[76:79], v[152:155], v[210:213], v[76:79]
	v_mfma_f32_16x16x32_bf16 v[8:11], v[174:177], v[206:209], v[8:11]
	v_mfma_f32_16x16x32_bf16 v[8:11], v[178:181], v[210:213], v[8:11]
	v_mfma_f32_16x16x32_bf16 v[52:55], v[148:151], v[214:217], v[52:55]
	v_mfma_f32_16x16x32_bf16 v[52:55], v[152:155], v[218:221], v[52:55]
	s_setprio 2
	s_barrier
	v_mfma_f32_16x16x32_bf16 v[4:7], v[174:177], v[214:217], v[4:7]
	v_mfma_f32_16x16x32_bf16 v[4:7], v[178:181], v[218:221], v[4:7]
	s_setprio 0
	s_cmp_gt_u32 s25, 29
	s_cbranch_scc0 .LBB0_828
